# hand-scheduled RWKV prompt scan (32 steps unrolled, sk/o DPP chains interleaved, counted LDS waits) + branch trampolines
# speedup vs baseline: 1.0855x; 1.0669x over previous
.LBB0_15:
	s_or_b64 exec, exec, s[0:1]
	s_lshr_b32 s48, s12, 6
	s_lshl_b32 s0, s2, 3
	s_add_i32 s16, s48, s0
	s_lshl_b32 s18, s46, 3
	s_cmpk_lt_i32 s16, 0x27e0
	s_cselect_b64 s[0:1], -1, 0
	v_writelane_b32 v252, s0, 2
	s_mov_b32 s8, s2
	s_mov_b32 s10, s14
	v_writelane_b32 v252, s1, 3
	s_lshl_b32 s0, s48, 14
	s_add_i32 s1, s0, 0
	s_bfe_u32 s0, s12, 0x10006
	s_cmpk_lt_i32 s2, 0x210
	v_writelane_b32 v252, s0, 4
	s_cselect_b64 s[2:3], -1, 0
	v_writelane_b32 v252, s2, 5
	s_lshl_b32 s0, s48, 13
	s_ashr_i32 s11, s14, 31
	v_writelane_b32 v252, s3, 6
	s_sub_i32 s2, s1, s0
	s_cmpk_lt_i32 s8, 0x400
	v_writelane_b32 v252, s1, 7
	s_cselect_b64 s[0:1], -1, 0
	v_writelane_b32 v252, s0, 8
	s_bfe_u32 s4, s12, 0x20006
	s_lshl_b32 s14, s4, 4
	v_writelane_b32 v252, s1, 9
	s_lshr_b32 s0, s12, 7
	s_and_b32 s1, s0, 0x1fffffe
	s_lshl_b32 s7, s48, 4
	s_lshl_b32 s13, s48, 3
	s_and_b32 s6, s48, 0x3fffffc
	s_lshl_b32 s3, s4, 3
	s_cmp_gt_u32 s1, s4
	s_cselect_b64 s[20:21], -1, 0
	v_writelane_b32 v252, s20, 10
	s_cmp_le_u32 s1, s4
	s_mov_b32 s73, 0
	v_writelane_b32 v252, s21, 11
	s_cselect_b64 s[20:21], -1, 0
	v_writelane_b32 v252, s20, 12
	s_lshl_b32 s1, s1, 4
	s_or_b32 s0, s0, 1
	v_writelane_b32 v252, s21, 13
	s_cmp_gt_u32 s0, s4
	v_writelane_b32 v252, s1, 14
	s_cselect_b64 s[20:21], -1, 0
	v_writelane_b32 v252, s20, 15
	s_cmp_le_u32 s0, s4
	s_mov_b32 s49, s73
	v_writelane_b32 v252, s21, 16
	s_cselect_b64 s[20:21], -1, 0
	v_writelane_b32 v252, s20, 17
	s_lshl_b32 s0, s0, 4
	s_or_b32 s5, s48, 3
	v_writelane_b32 v252, s21, 18
	v_writelane_b32 v252, s0, 19
	s_lshl_b32 s0, s6, 4
	s_or_b32 s1, s0, 16
	v_writelane_b32 v252, s1, 20
	v_writelane_b32 v252, s0, 21
	s_or_b32 s0, s0, 32
	v_writelane_b32 v252, s0, 22
	s_lshl_b32 s0, s5, 4
	s_cmpk_lt_i32 s8, 0x800
	v_writelane_b32 v252, s0, 23
	s_cselect_b64 s[0:1], -1, 0
	v_writelane_b32 v252, s0, 24
	s_mov_b32 s15, s73
	v_xor_b32_e32 v1, 1, v162
	v_writelane_b32 v252, s1, 25
	s_and_b32 s0, s7, 48
	v_writelane_b32 v252, s0, 26
	s_lshr_b32 s0, s12, 3
	s_and_b32 s0, s0, 0x1fffffe0
	s_cmpk_gt_i32 s8, 0x7f
	v_writelane_b32 v252, s0, 27
	s_cselect_b64 s[0:1], -1, 0
	v_cndmask_b32_e64 v0, 0, 1, s[0:1]
	s_cmpk_eq_i32 s46, 0x100
	v_readfirstlane_b32 s0, v0
	s_cselect_b32 s0, s0, 3
	s_lshr_b32 s72, s12, 8
	v_writelane_b32 v252, s0, 28
	s_add_i32 s0, s8, 0xffffff80
	v_writelane_b32 v252, s0, 29
	s_lshl_b32 s0, s72, 6
	v_writelane_b32 v252, s0, 30
	s_lshl_b32 s0, s72, 13
	v_writelane_b32 v252, s0, 31
	s_lshl_b32 s0, s4, 5
	s_lshl_b32 s33, s48, 10
	v_writelane_b32 v252, s0, 32
	s_lshl_b32 s0, s4, 12
	s_cmp_eq_u32 s72, 1
	v_writelane_b32 v252, s0, 33
	s_cselect_b64 s[0:1], -1, 0
	v_writelane_b32 v252, s0, 34
	s_cmpk_lt_u32 s12, 0x100
	s_cselect_b64 s[76:77], -1, 0
	v_writelane_b32 v252, s1, 35
	s_ashr_i32 s0, s8, 4
	v_writelane_b32 v252, s0, 36
	s_bfe_u32 s0, s8, 0x30001
	v_writelane_b32 v252, s0, 37
	s_and_b32 s0, s8, 1
	v_writelane_b32 v252, s0, 38
	s_lshl_b32 s0, s12, 3
	s_and_b32 s0, s0, 0xfffff800
	v_writelane_b32 v252, s0, 39
	s_and_b32 s0, s13, 0x1fffffe0
	v_writelane_b32 v252, s0, 40
	s_add_i32 s0, s3, s72
	v_writelane_b32 v252, s0, 41
	s_lshl_b32 s0, s72, 4
	v_writelane_b32 v252, s0, 42
	s_mul_i32 s0, s48, 0xffffe020
	s_add_i32 s20, s2, s0
	s_cmpk_gt_u32 s12, 0xff
	v_writelane_b32 v252, s2, 43
	s_cselect_b64 s[0:1], -1, 0
	v_writelane_b32 v252, s0, 44
	v_and_b32_e32 v0, 64, v162
	v_add_u32_e32 v0, 64, v0
	v_writelane_b32 v252, s1, 45
	s_lshl_b32 s0, s8, 5
	s_lshl_b32 s1, s48, 2
	s_add_i32 s1, s1, s0
	s_cmp_lt_i32 s1, 0x21000
	s_cselect_b64 s[22:23], -1, 0
	v_writelane_b32 v252, s22, 46
	s_lshl_b32 s53, s46, 5
	s_cmp_lt_i32 s1, 0x10000
	v_writelane_b32 v252, s23, 47
	v_writelane_b32 v252, s1, 48
	s_cselect_b64 s[22:23], -1, 0
	v_writelane_b32 v252, s22, 49
	s_cmpk_lt_i32 s16, 0x4200
	v_cmp_lt_i32_e32 vcc, v1, v0
	v_writelane_b32 v252, s23, 50
	s_cselect_b64 s[22:23], -1, 0
	v_writelane_b32 v252, s22, 51
	s_cmpk_lt_i32 s8, 0x100
	v_xor_b32_e32 v2, 2, v162
	v_writelane_b32 v252, s23, 52
	s_cselect_b64 s[22:23], -1, 0
	v_writelane_b32 v252, s22, 53
	s_and_b32 s1, s7, 16
	s_bitset1_b32 s1, 14
	v_writelane_b32 v252, s23, 54
	v_writelane_b32 v252, s7, 55
	s_ashr_i32 s9, s8, 31
	v_writelane_b32 v252, s1, 56
	s_lshr_b32 s1, s9, 29
	s_add_i32 s1, s8, s1
	s_ashr_i32 s2, s1, 3
	s_and_b32 s1, s1, -8
	v_writelane_b32 v252, s2, 57
	s_sub_i32 s1, s8, s1
	v_writelane_b32 v252, s1, 58
	s_addk_i32 s0, 0xc000
	v_writelane_b32 v252, s0, 59
	v_writelane_b32 v252, s13, 60
	s_and_b32 s0, s13, 0x1ffffff0
	s_ashr_i32 s47, s46, 31
	v_writelane_b32 v252, s0, 61
	s_lshl_b64 s[0:1], s[8:9], 9
	s_add_u32 s0, s0, 0x1b588000
	s_addc_u32 s1, s1, 0
	v_writelane_b32 v252, s0, 62
	v_cndmask_b32_e32 v1, v162, v1, vcc
	v_cmp_lt_i32_e32 vcc, v2, v0
	v_writelane_b32 v252, s1, 63
	s_lshl_b64 s[0:1], s[8:9], 5
	s_or_b32 s0, s0, s3
	s_lshl_b64 s[2:3], s[46:47], 9
	v_writelane_b32 v251, s2, 0
	v_xor_b32_e32 v3, 4, v162
	v_cndmask_b32_e32 v2, v162, v2, vcc
	v_writelane_b32 v251, s3, 1
	s_add_u32 s2, s0, s5
	s_addc_u32 s3, s1, 0
	s_lshl_b64 s[2:3], s[2:3], 10
	s_add_u32 s2, s2, 0x17588000
	s_addc_u32 s3, s3, 0
	v_writelane_b32 v251, s2, 2
	s_lshl_b32 s4, s4, 13
	v_cmp_lt_i32_e32 vcc, v3, v0
	v_writelane_b32 v251, s3, 3
	s_lshl_b64 s[2:3], s[8:9], 15
	s_or_b32 s7, s2, s4
	s_lshl_b64 s[4:5], s[46:47], 15
	v_writelane_b32 v251, s4, 4
	v_xor_b32_e32 v4, 8, v162
	v_cndmask_b32_e32 v3, v162, v3, vcc
	v_writelane_b32 v251, s5, 5
	s_lshl_b64 s[4:5], s[72:73], 12
	s_add_u32 s4, s7, s4
	s_addc_u32 s5, s3, s5
	s_add_u32 s0, s0, s6
	s_addc_u32 s1, s1, 0
	s_lshl_b64 s[0:1], s[0:1], 10
	v_writelane_b32 v251, s4, 6
	s_add_u32 s0, s0, 0x17588000
	s_addc_u32 s1, s1, 0
	v_writelane_b32 v251, s5, 7
	v_writelane_b32 v251, s0, 8
	v_cmp_lt_i32_e32 vcc, v4, v0
	v_xor_b32_e32 v5, 16, v162
	v_writelane_b32 v251, s1, 9
	s_lshl_b32 s0, s8, 6
	v_writelane_b32 v251, s0, 10
	s_lshl_b32 s0, s46, 6
	v_writelane_b32 v251, s0, 11
	s_lshl_b64 s[0:1], s[8:9], 14
	v_writelane_b32 v251, s0, 12
	v_cndmask_b32_e32 v4, v162, v4, vcc
	v_cmp_lt_i32_e32 vcc, v5, v0
	v_writelane_b32 v251, s1, 13
	s_lshl_b64 s[0:1], s[46:47], 14
	v_writelane_b32 v251, s0, 14
	v_xor_b32_e32 v6, 32, v162
	v_cndmask_b32_e32 v5, v162, v5, vcc
	v_writelane_b32 v251, s1, 15
	s_lshl_b64 s[0:1], s[48:49], 12
	s_add_u32 s0, s2, s0
	s_addc_u32 s1, s3, s1
	s_add_u32 s0, s0, 0x19588800
	s_addc_u32 s1, s1, 0
	v_writelane_b32 v251, s0, 16
	v_cmp_lt_i32_e32 vcc, v6, v0
	v_lshlrev_b32_e32 v163, 2, v1
	v_writelane_b32 v251, s1, 17
	s_lshl_b32 s0, s48, 7
	s_add_i32 s0, s0, 0
	v_writelane_b32 v251, s0, 18
	s_add_i32 s0, s10, 0xfffffe00
	v_writelane_b32 v251, s0, 19
	s_lshl_b32 s0, s72, 5
	v_writelane_b32 v251, s0, 20
	v_writelane_b32 v251, s10, 21
	s_add_u32 s0, s10, 0x1b588200
	v_cndmask_b32_e32 v0, v162, v6, vcc
	v_writelane_b32 v251, s11, 22
	v_writelane_b32 v251, s0, 23
	s_addc_u32 s0, 0, 0
	v_writelane_b32 v251, s0, 24
	s_lshl_b32 s0, s8, 11
	s_lshl_b32 s1, s48, 8
	s_add_i32 s0, s0, s1
	s_ashr_i32 s17, s16, 31
	v_writelane_b32 v251, s0, 25
	s_ashr_i32 s19, s18, 31
	s_lshl_b32 s80, s46, 11
	s_lshl_b64 s[0:1], s[16:17], 9
	s_add_u32 s0, s0, 0x11a40000
	v_writelane_b32 v251, s0, 26
	s_addc_u32 s0, s1, 0
	v_writelane_b32 v251, s0, 27
	v_writelane_b32 v251, s14, 28
	s_lshl_b64 s[0:1], s[16:17], 12
	s_or_b32 s0, s0, 0xc00
	v_writelane_b32 v251, s15, 29
	v_writelane_b32 v251, s0, 30
	s_lshl_b64 s[4:5], s[18:19], 9
	s_lshl_b64 s[56:57], s[18:19], 11
	v_writelane_b32 v251, s1, 31
	s_mul_i32 s0, s48, 0xffffffe4
	v_writelane_b32 v251, s20, 32
	s_add_i32 s0, s20, s0
	v_writelane_b32 v251, s0, 33
	v_writelane_b32 v251, s8, 34
	s_lshl_b32 s0, s8, 1
	v_lshlrev_b32_e32 v164, 2, v2
	v_writelane_b32 v251, s9, 35
	v_writelane_b32 v251, s0, 36
	s_lshl_b32 s0, s46, 1
	v_writelane_b32 v251, s0, 37
	s_add_i32 s0, 0, 0x11400
	v_writelane_b32 v251, s0, 38
	s_add_i32 s0, 0, 0x15c00
	v_writelane_b32 v251, s0, 39
	s_add_i32 s0, 0, 0x23fc0
	v_writelane_b32 v251, s0, 40
	s_add_i32 s0, 0, 0x23fc4
	v_writelane_b32 v251, s0, 41
	s_add_i32 s0, 0, 0x23ff0
	v_writelane_b32 v251, s0, 42
	v_writelane_b32 v251, s4, 43
	v_lshlrev_b32_e32 v165, 2, v3
	v_lshlrev_b32_e32 v166, 2, v4
	v_writelane_b32 v251, s5, 44
	s_lshl_b64 s[4:5], s[16:17], 10
	v_writelane_b32 v251, s4, 45
	v_lshlrev_b32_e32 v167, 2, v5
	v_lshlrev_b32_e32 v168, 2, v0
	v_writelane_b32 v251, s5, 46
	s_lshl_b64 s[4:5], s[18:19], 10
	v_writelane_b32 v251, s4, 47
	v_mov_b32_e32 v1, 0
	v_mov_b32_e32 v169, 0x358637bd
	v_writelane_b32 v251, s5, 48
	v_writelane_b32 v251, s16, 49
	s_lshl_b64 s[4:5], s[16:17], 11
	v_mov_b32_e32 v170, 0x260
	v_writelane_b32 v251, s17, 50
	v_writelane_b32 v251, s4, 51
	v_mov_b32_e32 v171, 0x3ab69700
	v_mov_b32_e32 v172, 0x1000
	v_writelane_b32 v251, s5, 52
	v_writelane_b32 v251, s18, 53
	s_lshl_b64 s[4:5], s[18:19], 12
	v_mov_b32_e32 v173, 0x2000
	v_writelane_b32 v251, s19, 54
	v_mov_b32_e32 v174, 0x4000
	v_mov_b32_e32 v175, 1
	v_mov_b32_e32 v176, 0x41b17218
	v_mov_b32_e32 v177, 0x1c00
	v_mov_b32_e32 v178, 0x7f000000
	v_mov_b64_e32 v[138:139], 0x318
	v_mov_b64_e32 v[140:141], 0x317
	v_mov_b32_e32 v179, 0x3000
	v_mov_b32_e32 v180, 0x6000
	v_mov_b32_e32 v181, 0x9000
	s_movk_i32 s49, 0xc00
	s_mov_b32 s74, 0x800000
	s_mov_b32 s81, 0xe8c0000
	s_movk_i32 s78, 0x7fff
	s_movk_i32 s79, 0x2600
	s_mov_b32 s82, 0xbfb8aa3b
	s_mov_b32 s83, 0x3f317217
	s_mov_b32 s92, 0x7f800000
	s_mov_b32 s93, 0xf800000
	s_add_i32 s66, 0, 0x18000
	s_movk_i32 s67, 0x1800
	s_mov_b32 s2, 0x43000000
	s_mov_b32 s3, 0x42b17217
	s_mov_b32 s52, 0xc1880000
	s_mov_b32 s0, 0
	v_writelane_b32 v251, s4, 55
	s_mov_b64 s[54:55], 0x80
	s_mov_b64 s[50:51], 0x200
	s_mov_b64 s[96:97], 0x400
	s_mov_b32 s75, s80
	s_barrier
	v_writelane_b32 v251, s5, 56
	s_branch .LBB0_19
.Lend_top:
	s_endpgm
.LBB0_16:
	s_or_b64 exec, exec, s[8:9]
	s_waitcnt vmcnt(0)

.LBB0_421:
	s_or_b64 exec, exec, s[0:1]
	v_readlane_b32 s6, v252, 0
	v_readlane_b32 s7, v252, 1
	s_mov_b64 s[0:1], s[6:7]
	v_readlane_b32 s8, v250, 5
	s_waitcnt lgkmcnt(0)
	s_barrier
	v_readlane_b32 s9, v250, 6
	s_load_dwordx2 s[0:1], s[0:1], 0x158
	s_and_b64 s[4:5], s[8:9], exec
	s_mov_b64 s[4:5], s[6:7]
	s_load_dwordx2 s[4:5], s[4:5], 0x158
	s_cselect_b32 s6, 64, 0
	v_writelane_b32 v250, s6, 12
	s_lshl_b32 s6, s6, 2
	s_waitcnt lgkmcnt(0)
	s_add_u32 s0, s0, s6
	s_addc_u32 s1, s1, 0
	v_writelane_b32 v250, s0, 13
	v_mov_b32_e32 v0, v162
	s_mov_b32 s71, s73
	v_writelane_b32 v250, s1, 14
	s_add_u32 s0, s4, s6
	s_addc_u32 s1, s5, 0
	v_writelane_b32 v250, s0, 15
	v_sub_u32_e32 v0, 0, v0
	v_readlane_b32 s24, v252, 28
	v_writelane_b32 v250, s1, 16
	v_readlane_b32 s0, v251, 21
	v_readlane_b32 s1, v251, 22
	s_nop 0
	v_cmp_eq_u32_e64 s[0:1], s0, v0
	s_nop 1
	v_writelane_b32 v250, s0, 10
	s_nop 1
	v_writelane_b32 v250, s1, 11
	s_and_b64 s[0:1], s[8:9], exec
	s_cselect_b32 s0, 0x4000, 0
	v_writelane_b32 v250, s0, 5
	s_cselect_b32 s0, 8, 0
	v_writelane_b32 v250, s0, 17
	s_cselect_b32 s0, 0x800, 0
	v_writelane_b32 v250, s0, 18
	s_cselect_b32 s0, 0x80, 0
	s_mov_b32 s1, s73
	v_writelane_b32 v250, s0, 19
	s_nop 1
	v_writelane_b32 v250, s1, 20
	s_cselect_b32 s0, 0x400, 0
	v_writelane_b32 v250, s0, 21
	s_cselect_b32 s0, 0x200000, 0
	v_writelane_b32 v250, s0, 22
	s_cselect_b32 s0, 0x200, 0
	v_writelane_b32 v250, s0, 23
	v_writelane_b32 v250, s70, 8
	s_nop 1
	v_writelane_b32 v250, s71, 9
	s_branch .LBB0_425
.Ltramp_16:
	s_branch .LBB0_16
.Ltramp_17:
	s_branch .LBB0_17
.Ltramp_18:
	s_branch .LBB0_18
.LBB0_422:
	s_or_b64 exec, exec, s[6:7]

.LBB0_608:
	s_and_b64 vcc, exec, s[36:37]
	s_cbranch_vccz .Lrw_fast
	s_setprio 3
	ds_read_b128 v[48:51], v124
	ds_read_b128 v[40:43], v124 offset:16
	ds_read_b128 v[72:75], v124 offset:256
	ds_read_b128 v[76:79], v124 offset:272
	ds_read_b128 v[68:71], v124 offset:512
	ds_read_b128 v[56:59], v124 offset:528
	ds_read_b128 v[64:67], v124 offset:768
	ds_read_b128 v[60:63], v124 offset:784
	ds_read_b128 v[44:47], v124 offset:1024
	ds_read_b128 v[52:55], v124 offset:1040
	v_lshlrev_b32_e32 v131, 2, v112
	v_add_u32_e32 v135, s72, v131
	ds_read_b32 v0, v135 offset:1280
	v_add_u32_e32 v136, v129, v131
	s_mov_b32 s58, 0
	v_mov_b32_e32 v134, 0
	s_movk_i32 s95, 0x300
	v_mov_b32_e32 v137, v123
	v_mov_b32_e32 v133, 0
	v_mov_b32_e32 v132, 0
	v_mov_b32_e32 v131, 0
	v_mov_b32_e32 v142, 0

.Lrw_fast:
	s_setprio 3
	v_lshlrev_b32_e32 v131, 2, v112
	v_add_u32_e32 v135, s72, v131
	ds_read_b128 v[76:79], v124 offset:272
	ds_read_b128 v[72:75], v124 offset:256
	ds_read_b128 v[68:71], v124 offset:512
	ds_read_b128 v[56:59], v124 offset:528
	ds_read_b32 v0, v135 offset:1280
	ds_read_b128 v[64:67], v124 offset:768
	ds_read_b128 v[60:63], v124 offset:784
	ds_read_b128 v[48:51], v124 offset:0
	ds_read_b128 v[40:43], v124 offset:16
	ds_read_b128 v[52:55], v124 offset:1040
	ds_read_b128 v[44:47], v124 offset:1024
	ds_read_b128 v[156:159], v124 offset:1808
	ds_read_b128 v[152:155], v124 offset:1792
	ds_read_b128 v[182:185], v124 offset:2048
	ds_read_b128 v[186:189], v124 offset:2064
	ds_read_b32 v160, v135 offset:2816
	ds_read_b128 v[190:193], v124 offset:2304
	ds_read_b128 v[194:197], v124 offset:2320
	ds_read_b128 v[144:147], v124 offset:1536
	ds_read_b128 v[148:151], v124 offset:1552
	ds_read_b128 v[202:205], v124 offset:2576
	ds_read_b128 v[198:201], v124 offset:2560
	s_waitcnt lgkmcnt(11)
	v_pk_mul_f32 v[76:77], v[32:33], v[76:77]
	v_pk_mul_f32 v[78:79], v[34:35], v[78:79]
	v_pk_fma_f32 v[72:73], v[36:37], v[72:73], v[76:77]
	v_pk_fma_f32 v[74:75], v[38:39], v[74:75], v[78:79]
	v_pk_add_f32 v[72:73], v[72:73], v[74:75]
	v_add_f32_e32 v142, v72, v73
	s_nop 1
	v_add_f32_dpp v142, v142, v142 quad_perm:[1,0,3,2] row_mask:0xf bank_mask:0xf bound_ctrl:1
	s_nop 1
	v_add_f32_dpp v142, v142, v142 quad_perm:[2,3,0,1] row_mask:0xf bank_mask:0xf bound_ctrl:1
	s_nop 1
	v_add_f32_dpp v142, v142, v142 row_half_mirror row_mask:0xf bank_mask:0xf bound_ctrl:1
	v_pk_mul_f32 v[68:69], v[68:69], v[142:143] op_sel_hi:[1,0]
	v_pk_mul_f32 v[70:71], v[70:71], v[142:143] op_sel_hi:[1,0]
	v_pk_mul_f32 v[56:57], v[56:57], v[142:143] op_sel_hi:[1,0]
	v_pk_mul_f32 v[58:59], v[58:59], v[142:143] op_sel_hi:[1,0]
	v_pk_fma_f32 v[64:65], v[64:65], v[0:1], v[68:69] op_sel_hi:[1,0,1] neg_lo:[0,0,1] neg_hi:[0,0,1]
	v_pk_fma_f32 v[66:67], v[66:67], v[0:1], v[70:71] op_sel_hi:[1,0,1] neg_lo:[0,0,1] neg_hi:[0,0,1]
	v_pk_fma_f32 v[60:61], v[60:61], v[0:1], v[56:57] op_sel_hi:[1,0,1] neg_lo:[0,0,1] neg_hi:[0,0,1]
	v_pk_fma_f32 v[62:63], v[62:63], v[0:1], v[58:59] op_sel_hi:[1,0,1] neg_lo:[0,0,1] neg_hi:[0,0,1]
	v_pk_fma_f32 v[36:37], v[36:37], v[48:49], v[64:65]
	v_pk_fma_f32 v[38:39], v[38:39], v[50:51], v[66:67]
	v_pk_fma_f32 v[32:33], v[32:33], v[40:41], v[60:61]
	v_pk_fma_f32 v[34:35], v[34:35], v[42:43], v[62:63]
	s_waitcnt lgkmcnt(2)
	v_pk_mul_f32 v[156:157], v[32:33], v[156:157]
	v_pk_mul_f32 v[52:53], v[32:33], v[52:53]
	v_pk_mul_f32 v[158:159], v[34:35], v[158:159]
	v_pk_mul_f32 v[54:55], v[34:35], v[54:55]
	v_pk_fma_f32 v[152:153], v[36:37], v[152:153], v[156:157]
	v_pk_fma_f32 v[44:45], v[36:37], v[44:45], v[52:53]
	v_pk_fma_f32 v[154:155], v[38:39], v[154:155], v[158:159]
	v_pk_fma_f32 v[46:47], v[38:39], v[46:47], v[54:55]
	v_pk_add_f32 v[152:153], v[152:153], v[154:155]
	v_pk_add_f32 v[44:45], v[44:45], v[46:47]
	v_add_f32_e32 v142, v152, v153
	v_add_f32_e32 v143, v44, v45
	ds_read_b128 v[76:79], v124 offset:3344
	v_add_f32_dpp v142, v142, v142 quad_perm:[1,0,3,2] row_mask:0xf bank_mask:0xf bound_ctrl:1
	v_add_f32_dpp v143, v143, v143 quad_perm:[1,0,3,2] row_mask:0xf bank_mask:0xf bound_ctrl:1
	ds_read_b128 v[72:75], v124 offset:3328
	v_add_f32_dpp v142, v142, v142 quad_perm:[2,3,0,1] row_mask:0xf bank_mask:0xf bound_ctrl:1
	v_add_f32_dpp v143, v143, v143 quad_perm:[2,3,0,1] row_mask:0xf bank_mask:0xf bound_ctrl:1
	ds_read_b128 v[68:71], v124 offset:3584
	v_add_f32_dpp v142, v142, v142 row_half_mirror row_mask:0xf bank_mask:0xf bound_ctrl:1
	v_add_f32_dpp v143, v143, v143 row_half_mirror row_mask:0xf bank_mask:0xf bound_ctrl:1
	ds_read_b128 v[56:59], v124 offset:3600
	ds_read_b32 v0, v135 offset:4352
	ds_read_b128 v[64:67], v124 offset:3840
	ds_read_b128 v[60:63], v124 offset:3856
	ds_read_b128 v[48:51], v124 offset:3072
	ds_read_b128 v[40:43], v124 offset:3088
	v_pk_mul_f32 v[182:183], v[182:183], v[142:143] op_sel_hi:[1,0]
	v_pk_mul_f32 v[184:185], v[184:185], v[142:143] op_sel_hi:[1,0]
	s_mov_b32 vcc_lo, 0x1010101
	v_pk_mul_f32 v[186:187], v[186:187], v[142:143] op_sel_hi:[1,0]
	v_pk_mul_f32 v[188:189], v[188:189], v[142:143] op_sel_hi:[1,0]
	s_mov_b32 vcc_hi, 0x1010101
	v_pk_fma_f32 v[190:191], v[190:191], v[160:161], v[182:183] op_sel_hi:[1,0,1] neg_lo:[0,0,1] neg_hi:[0,0,1]
	v_pk_fma_f32 v[192:193], v[192:193], v[160:161], v[184:185] op_sel_hi:[1,0,1] neg_lo:[0,0,1] neg_hi:[0,0,1]
	v_cndmask_b32_e32 v134, v134, v143, vcc
	v_pk_fma_f32 v[194:195], v[194:195], v[160:161], v[186:187] op_sel_hi:[1,0,1] neg_lo:[0,0,1] neg_hi:[0,0,1]
	v_pk_fma_f32 v[196:197], v[196:197], v[160:161], v[188:189] op_sel_hi:[1,0,1] neg_lo:[0,0,1] neg_hi:[0,0,1]
	ds_read_b128 v[52:55], v124 offset:4112
	ds_read_b128 v[44:47], v124 offset:4096
	v_pk_fma_f32 v[36:37], v[36:37], v[144:145], v[190:191]
	v_pk_fma_f32 v[38:39], v[38:39], v[146:147], v[192:193]
	v_pk_fma_f32 v[32:33], v[32:33], v[148:149], v[194:195]
	v_pk_fma_f32 v[34:35], v[34:35], v[150:151], v[196:197]
	s_waitcnt lgkmcnt(2)
	v_pk_mul_f32 v[76:77], v[32:33], v[76:77]
	v_pk_mul_f32 v[202:203], v[32:33], v[202:203]
	v_pk_mul_f32 v[78:79], v[34:35], v[78:79]
	v_pk_mul_f32 v[204:205], v[34:35], v[204:205]
	v_pk_fma_f32 v[72:73], v[36:37], v[72:73], v[76:77]
	v_pk_fma_f32 v[198:199], v[36:37], v[198:199], v[202:203]
	v_pk_fma_f32 v[74:75], v[38:39], v[74:75], v[78:79]
	v_pk_fma_f32 v[200:201], v[38:39], v[200:201], v[204:205]
	v_pk_add_f32 v[72:73], v[72:73], v[74:75]
	v_pk_add_f32 v[198:199], v[198:199], v[200:201]
	v_add_f32_e32 v142, v72, v73
	v_add_f32_e32 v143, v198, v199
	ds_read_b128 v[156:159], v124 offset:4880
	v_add_f32_dpp v142, v142, v142 quad_perm:[1,0,3,2] row_mask:0xf bank_mask:0xf bound_ctrl:1
	v_add_f32_dpp v143, v143, v143 quad_perm:[1,0,3,2] row_mask:0xf bank_mask:0xf bound_ctrl:1
	ds_read_b128 v[152:155], v124 offset:4864
	v_add_f32_dpp v142, v142, v142 quad_perm:[2,3,0,1] row_mask:0xf bank_mask:0xf bound_ctrl:1
	v_add_f32_dpp v143, v143, v143 quad_perm:[2,3,0,1] row_mask:0xf bank_mask:0xf bound_ctrl:1
	ds_read_b128 v[182:185], v124 offset:5120
	v_add_f32_dpp v142, v142, v142 row_half_mirror row_mask:0xf bank_mask:0xf bound_ctrl:1
	v_add_f32_dpp v143, v143, v143 row_half_mirror row_mask:0xf bank_mask:0xf bound_ctrl:1
	ds_read_b128 v[186:189], v124 offset:5136
	ds_read_b32 v160, v135 offset:5888
	ds_read_b128 v[190:193], v124 offset:5376
	ds_read_b128 v[194:197], v124 offset:5392
	ds_read_b128 v[144:147], v124 offset:4608
	ds_read_b128 v[148:151], v124 offset:4624
	v_pk_mul_f32 v[68:69], v[68:69], v[142:143] op_sel_hi:[1,0]
	v_pk_mul_f32 v[70:71], v[70:71], v[142:143] op_sel_hi:[1,0]
	s_mov_b32 vcc_lo, 0x2020202
	v_pk_mul_f32 v[56:57], v[56:57], v[142:143] op_sel_hi:[1,0]
	v_pk_mul_f32 v[58:59], v[58:59], v[142:143] op_sel_hi:[1,0]
	s_mov_b32 vcc_hi, 0x2020202
	v_pk_fma_f32 v[64:65], v[64:65], v[0:1], v[68:69] op_sel_hi:[1,0,1] neg_lo:[0,0,1] neg_hi:[0,0,1]
	v_pk_fma_f32 v[66:67], v[66:67], v[0:1], v[70:71] op_sel_hi:[1,0,1] neg_lo:[0,0,1] neg_hi:[0,0,1]
	v_cndmask_b32_e32 v134, v134, v143, vcc
	v_pk_fma_f32 v[60:61], v[60:61], v[0:1], v[56:57] op_sel_hi:[1,0,1] neg_lo:[0,0,1] neg_hi:[0,0,1]
	v_pk_fma_f32 v[62:63], v[62:63], v[0:1], v[58:59] op_sel_hi:[1,0,1] neg_lo:[0,0,1] neg_hi:[0,0,1]
	ds_read_b128 v[202:205], v124 offset:5648
	ds_read_b128 v[198:201], v124 offset:5632
	v_pk_fma_f32 v[36:37], v[36:37], v[48:49], v[64:65]
	v_pk_fma_f32 v[38:39], v[38:39], v[50:51], v[66:67]
	v_pk_fma_f32 v[32:33], v[32:33], v[40:41], v[60:61]
	v_pk_fma_f32 v[34:35], v[34:35], v[42:43], v[62:63]
	s_waitcnt lgkmcnt(2)
	v_pk_mul_f32 v[156:157], v[32:33], v[156:157]
	v_pk_mul_f32 v[52:53], v[32:33], v[52:53]
	v_pk_mul_f32 v[158:159], v[34:35], v[158:159]
	v_pk_mul_f32 v[54:55], v[34:35], v[54:55]
	v_pk_fma_f32 v[152:153], v[36:37], v[152:153], v[156:157]
	v_pk_fma_f32 v[44:45], v[36:37], v[44:45], v[52:53]
	v_pk_fma_f32 v[154:155], v[38:39], v[154:155], v[158:159]
	v_pk_fma_f32 v[46:47], v[38:39], v[46:47], v[54:55]
	v_pk_add_f32 v[152:153], v[152:153], v[154:155]
	v_pk_add_f32 v[44:45], v[44:45], v[46:47]
	v_add_f32_e32 v142, v152, v153
	v_add_f32_e32 v143, v44, v45
	ds_read_b128 v[76:79], v124 offset:6416
	v_add_f32_dpp v142, v142, v142 quad_perm:[1,0,3,2] row_mask:0xf bank_mask:0xf bound_ctrl:1
	v_add_f32_dpp v143, v143, v143 quad_perm:[1,0,3,2] row_mask:0xf bank_mask:0xf bound_ctrl:1
	ds_read_b128 v[72:75], v124 offset:6400
	v_add_f32_dpp v142, v142, v142 quad_perm:[2,3,0,1] row_mask:0xf bank_mask:0xf bound_ctrl:1
	v_add_f32_dpp v143, v143, v143 quad_perm:[2,3,0,1] row_mask:0xf bank_mask:0xf bound_ctrl:1
	ds_read_b128 v[68:71], v124 offset:6656
	v_add_f32_dpp v142, v142, v142 row_half_mirror row_mask:0xf bank_mask:0xf bound_ctrl:1
	v_add_f32_dpp v143, v143, v143 row_half_mirror row_mask:0xf bank_mask:0xf bound_ctrl:1
	ds_read_b128 v[56:59], v124 offset:6672
	ds_read_b32 v0, v135 offset:7424
	ds_read_b128 v[64:67], v124 offset:6912
	ds_read_b128 v[60:63], v124 offset:6928
	ds_read_b128 v[48:51], v124 offset:6144
	ds_read_b128 v[40:43], v124 offset:6160
	v_pk_mul_f32 v[182:183], v[182:183], v[142:143] op_sel_hi:[1,0]
	v_pk_mul_f32 v[184:185], v[184:185], v[142:143] op_sel_hi:[1,0]
	s_mov_b32 vcc_lo, 0x4040404
	v_pk_mul_f32 v[186:187], v[186:187], v[142:143] op_sel_hi:[1,0]
	v_pk_mul_f32 v[188:189], v[188:189], v[142:143] op_sel_hi:[1,0]
	s_mov_b32 vcc_hi, 0x4040404
	v_pk_fma_f32 v[190:191], v[190:191], v[160:161], v[182:183] op_sel_hi:[1,0,1] neg_lo:[0,0,1] neg_hi:[0,0,1]
	v_pk_fma_f32 v[192:193], v[192:193], v[160:161], v[184:185] op_sel_hi:[1,0,1] neg_lo:[0,0,1] neg_hi:[0,0,1]
	v_cndmask_b32_e32 v134, v134, v143, vcc
	v_pk_fma_f32 v[194:195], v[194:195], v[160:161], v[186:187] op_sel_hi:[1,0,1] neg_lo:[0,0,1] neg_hi:[0,0,1]
	v_pk_fma_f32 v[196:197], v[196:197], v[160:161], v[188:189] op_sel_hi:[1,0,1] neg_lo:[0,0,1] neg_hi:[0,0,1]
	ds_read_b128 v[52:55], v124 offset:7184
	ds_read_b128 v[44:47], v124 offset:7168
	v_pk_fma_f32 v[36:37], v[36:37], v[144:145], v[190:191]
	v_pk_fma_f32 v[38:39], v[38:39], v[146:147], v[192:193]
	v_pk_fma_f32 v[32:33], v[32:33], v[148:149], v[194:195]
	v_pk_fma_f32 v[34:35], v[34:35], v[150:151], v[196:197]
	s_waitcnt lgkmcnt(2)
	v_pk_mul_f32 v[76:77], v[32:33], v[76:77]
	v_pk_mul_f32 v[202:203], v[32:33], v[202:203]
	v_pk_mul_f32 v[78:79], v[34:35], v[78:79]
	v_pk_mul_f32 v[204:205], v[34:35], v[204:205]
	v_pk_fma_f32 v[72:73], v[36:37], v[72:73], v[76:77]
	v_pk_fma_f32 v[198:199], v[36:37], v[198:199], v[202:203]
	v_pk_fma_f32 v[74:75], v[38:39], v[74:75], v[78:79]
	v_pk_fma_f32 v[200:201], v[38:39], v[200:201], v[204:205]
	v_pk_add_f32 v[72:73], v[72:73], v[74:75]
	v_pk_add_f32 v[198:199], v[198:199], v[200:201]
	v_add_f32_e32 v142, v72, v73
	v_add_f32_e32 v143, v198, v199
	ds_read_b128 v[156:159], v124 offset:7952
	v_add_f32_dpp v142, v142, v142 quad_perm:[1,0,3,2] row_mask:0xf bank_mask:0xf bound_ctrl:1
	v_add_f32_dpp v143, v143, v143 quad_perm:[1,0,3,2] row_mask:0xf bank_mask:0xf bound_ctrl:1
	ds_read_b128 v[152:155], v124 offset:7936
	v_add_f32_dpp v142, v142, v142 quad_perm:[2,3,0,1] row_mask:0xf bank_mask:0xf bound_ctrl:1
	v_add_f32_dpp v143, v143, v143 quad_perm:[2,3,0,1] row_mask:0xf bank_mask:0xf bound_ctrl:1
	ds_read_b128 v[182:185], v124 offset:8192
	v_add_f32_dpp v142, v142, v142 row_half_mirror row_mask:0xf bank_mask:0xf bound_ctrl:1
	v_add_f32_dpp v143, v143, v143 row_half_mirror row_mask:0xf bank_mask:0xf bound_ctrl:1
	ds_read_b128 v[186:189], v124 offset:8208
	ds_read_b32 v160, v135 offset:8960
	ds_read_b128 v[190:193], v124 offset:8448
	ds_read_b128 v[194:197], v124 offset:8464
	ds_read_b128 v[144:147], v124 offset:7680
	ds_read_b128 v[148:151], v124 offset:7696
	v_pk_mul_f32 v[68:69], v[68:69], v[142:143] op_sel_hi:[1,0]
	v_pk_mul_f32 v[70:71], v[70:71], v[142:143] op_sel_hi:[1,0]
	s_mov_b32 vcc_lo, 0x8080808
	v_pk_mul_f32 v[56:57], v[56:57], v[142:143] op_sel_hi:[1,0]
	v_pk_mul_f32 v[58:59], v[58:59], v[142:143] op_sel_hi:[1,0]
	s_mov_b32 vcc_hi, 0x8080808
	v_pk_fma_f32 v[64:65], v[64:65], v[0:1], v[68:69] op_sel_hi:[1,0,1] neg_lo:[0,0,1] neg_hi:[0,0,1]
	v_pk_fma_f32 v[66:67], v[66:67], v[0:1], v[70:71] op_sel_hi:[1,0,1] neg_lo:[0,0,1] neg_hi:[0,0,1]
	v_cndmask_b32_e32 v134, v134, v143, vcc
	v_pk_fma_f32 v[60:61], v[60:61], v[0:1], v[56:57] op_sel_hi:[1,0,1] neg_lo:[0,0,1] neg_hi:[0,0,1]
	v_pk_fma_f32 v[62:63], v[62:63], v[0:1], v[58:59] op_sel_hi:[1,0,1] neg_lo:[0,0,1] neg_hi:[0,0,1]
	ds_read_b128 v[202:205], v124 offset:8720
	ds_read_b128 v[198:201], v124 offset:8704
	v_pk_fma_f32 v[36:37], v[36:37], v[48:49], v[64:65]
	v_pk_fma_f32 v[38:39], v[38:39], v[50:51], v[66:67]
	v_pk_fma_f32 v[32:33], v[32:33], v[40:41], v[60:61]
	v_pk_fma_f32 v[34:35], v[34:35], v[42:43], v[62:63]
	s_waitcnt lgkmcnt(2)
	v_pk_mul_f32 v[156:157], v[32:33], v[156:157]
	v_pk_mul_f32 v[52:53], v[32:33], v[52:53]
	v_pk_mul_f32 v[158:159], v[34:35], v[158:159]
	v_pk_mul_f32 v[54:55], v[34:35], v[54:55]
	v_pk_fma_f32 v[152:153], v[36:37], v[152:153], v[156:157]
	v_pk_fma_f32 v[44:45], v[36:37], v[44:45], v[52:53]
	v_pk_fma_f32 v[154:155], v[38:39], v[154:155], v[158:159]
	v_pk_fma_f32 v[46:47], v[38:39], v[46:47], v[54:55]
	v_pk_add_f32 v[152:153], v[152:153], v[154:155]
	v_pk_add_f32 v[44:45], v[44:45], v[46:47]
	v_add_f32_e32 v142, v152, v153
	v_add_f32_e32 v143, v44, v45
	ds_read_b128 v[76:79], v124 offset:9488
	v_add_f32_dpp v142, v142, v142 quad_perm:[1,0,3,2] row_mask:0xf bank_mask:0xf bound_ctrl:1
	v_add_f32_dpp v143, v143, v143 quad_perm:[1,0,3,2] row_mask:0xf bank_mask:0xf bound_ctrl:1
	ds_read_b128 v[72:75], v124 offset:9472
	v_add_f32_dpp v142, v142, v142 quad_perm:[2,3,0,1] row_mask:0xf bank_mask:0xf bound_ctrl:1
	v_add_f32_dpp v143, v143, v143 quad_perm:[2,3,0,1] row_mask:0xf bank_mask:0xf bound_ctrl:1
	ds_read_b128 v[68:71], v124 offset:9728
	v_add_f32_dpp v142, v142, v142 row_half_mirror row_mask:0xf bank_mask:0xf bound_ctrl:1
	v_add_f32_dpp v143, v143, v143 row_half_mirror row_mask:0xf bank_mask:0xf bound_ctrl:1
	ds_read_b128 v[56:59], v124 offset:9744
	ds_read_b32 v0, v135 offset:10496
	ds_read_b128 v[64:67], v124 offset:9984
	ds_read_b128 v[60:63], v124 offset:10000
	ds_read_b128 v[48:51], v124 offset:9216
	ds_read_b128 v[40:43], v124 offset:9232
	v_pk_mul_f32 v[182:183], v[182:183], v[142:143] op_sel_hi:[1,0]
	v_pk_mul_f32 v[184:185], v[184:185], v[142:143] op_sel_hi:[1,0]
	s_mov_b32 vcc_lo, 0x10101010
	v_pk_mul_f32 v[186:187], v[186:187], v[142:143] op_sel_hi:[1,0]
	v_pk_mul_f32 v[188:189], v[188:189], v[142:143] op_sel_hi:[1,0]
	s_mov_b32 vcc_hi, 0x10101010
	v_pk_fma_f32 v[190:191], v[190:191], v[160:161], v[182:183] op_sel_hi:[1,0,1] neg_lo:[0,0,1] neg_hi:[0,0,1]
	v_pk_fma_f32 v[192:193], v[192:193], v[160:161], v[184:185] op_sel_hi:[1,0,1] neg_lo:[0,0,1] neg_hi:[0,0,1]
	v_cndmask_b32_e32 v134, v134, v143, vcc
	v_pk_fma_f32 v[194:195], v[194:195], v[160:161], v[186:187] op_sel_hi:[1,0,1] neg_lo:[0,0,1] neg_hi:[0,0,1]
	v_pk_fma_f32 v[196:197], v[196:197], v[160:161], v[188:189] op_sel_hi:[1,0,1] neg_lo:[0,0,1] neg_hi:[0,0,1]
	ds_read_b128 v[52:55], v124 offset:10256
	ds_read_b128 v[44:47], v124 offset:10240
	v_pk_fma_f32 v[36:37], v[36:37], v[144:145], v[190:191]
	v_pk_fma_f32 v[38:39], v[38:39], v[146:147], v[192:193]
	v_pk_fma_f32 v[32:33], v[32:33], v[148:149], v[194:195]
	v_pk_fma_f32 v[34:35], v[34:35], v[150:151], v[196:197]
	s_waitcnt lgkmcnt(2)
	v_pk_mul_f32 v[76:77], v[32:33], v[76:77]
	v_pk_mul_f32 v[202:203], v[32:33], v[202:203]
	v_pk_mul_f32 v[78:79], v[34:35], v[78:79]
	v_pk_mul_f32 v[204:205], v[34:35], v[204:205]
	v_pk_fma_f32 v[72:73], v[36:37], v[72:73], v[76:77]
	v_pk_fma_f32 v[198:199], v[36:37], v[198:199], v[202:203]
	v_pk_fma_f32 v[74:75], v[38:39], v[74:75], v[78:79]
	v_pk_fma_f32 v[200:201], v[38:39], v[200:201], v[204:205]
	v_pk_add_f32 v[72:73], v[72:73], v[74:75]
	v_pk_add_f32 v[198:199], v[198:199], v[200:201]
	v_add_f32_e32 v142, v72, v73
	v_add_f32_e32 v143, v198, v199
	ds_read_b128 v[156:159], v124 offset:11024
	v_add_f32_dpp v142, v142, v142 quad_perm:[1,0,3,2] row_mask:0xf bank_mask:0xf bound_ctrl:1
	v_add_f32_dpp v143, v143, v143 quad_perm:[1,0,3,2] row_mask:0xf bank_mask:0xf bound_ctrl:1
	ds_read_b128 v[152:155], v124 offset:11008
	v_add_f32_dpp v142, v142, v142 quad_perm:[2,3,0,1] row_mask:0xf bank_mask:0xf bound_ctrl:1
	v_add_f32_dpp v143, v143, v143 quad_perm:[2,3,0,1] row_mask:0xf bank_mask:0xf bound_ctrl:1
	ds_read_b128 v[182:185], v124 offset:11264
	v_add_f32_dpp v142, v142, v142 row_half_mirror row_mask:0xf bank_mask:0xf bound_ctrl:1
	v_add_f32_dpp v143, v143, v143 row_half_mirror row_mask:0xf bank_mask:0xf bound_ctrl:1
	ds_read_b128 v[186:189], v124 offset:11280
	ds_read_b32 v160, v135 offset:12032
	ds_read_b128 v[190:193], v124 offset:11520
	ds_read_b128 v[194:197], v124 offset:11536
	ds_read_b128 v[144:147], v124 offset:10752
	ds_read_b128 v[148:151], v124 offset:10768
	v_pk_mul_f32 v[68:69], v[68:69], v[142:143] op_sel_hi:[1,0]
	v_pk_mul_f32 v[70:71], v[70:71], v[142:143] op_sel_hi:[1,0]
	s_mov_b32 vcc_lo, 0x20202020
	v_pk_mul_f32 v[56:57], v[56:57], v[142:143] op_sel_hi:[1,0]
	v_pk_mul_f32 v[58:59], v[58:59], v[142:143] op_sel_hi:[1,0]
	s_mov_b32 vcc_hi, 0x20202020
	v_pk_fma_f32 v[64:65], v[64:65], v[0:1], v[68:69] op_sel_hi:[1,0,1] neg_lo:[0,0,1] neg_hi:[0,0,1]
	v_pk_fma_f32 v[66:67], v[66:67], v[0:1], v[70:71] op_sel_hi:[1,0,1] neg_lo:[0,0,1] neg_hi:[0,0,1]
	v_cndmask_b32_e32 v134, v134, v143, vcc
	v_pk_fma_f32 v[60:61], v[60:61], v[0:1], v[56:57] op_sel_hi:[1,0,1] neg_lo:[0,0,1] neg_hi:[0,0,1]
	v_pk_fma_f32 v[62:63], v[62:63], v[0:1], v[58:59] op_sel_hi:[1,0,1] neg_lo:[0,0,1] neg_hi:[0,0,1]
	ds_read_b128 v[202:205], v124 offset:11792
	ds_read_b128 v[198:201], v124 offset:11776
	v_pk_fma_f32 v[36:37], v[36:37], v[48:49], v[64:65]
	v_pk_fma_f32 v[38:39], v[38:39], v[50:51], v[66:67]
	v_pk_fma_f32 v[32:33], v[32:33], v[40:41], v[60:61]
	v_pk_fma_f32 v[34:35], v[34:35], v[42:43], v[62:63]
	s_waitcnt lgkmcnt(2)
	v_pk_mul_f32 v[156:157], v[32:33], v[156:157]
	v_pk_mul_f32 v[52:53], v[32:33], v[52:53]
	v_pk_mul_f32 v[158:159], v[34:35], v[158:159]
	v_pk_mul_f32 v[54:55], v[34:35], v[54:55]
	v_pk_fma_f32 v[152:153], v[36:37], v[152:153], v[156:157]
	v_pk_fma_f32 v[44:45], v[36:37], v[44:45], v[52:53]
	v_pk_fma_f32 v[154:155], v[38:39], v[154:155], v[158:159]
	v_pk_fma_f32 v[46:47], v[38:39], v[46:47], v[54:55]
	v_pk_add_f32 v[152:153], v[152:153], v[154:155]
	v_pk_add_f32 v[44:45], v[44:45], v[46:47]
	v_add_f32_e32 v142, v152, v153
	v_add_f32_e32 v143, v44, v45
	ds_read_b128 v[76:79], v124 offset:12560
	v_add_f32_dpp v142, v142, v142 quad_perm:[1,0,3,2] row_mask:0xf bank_mask:0xf bound_ctrl:1
	v_add_f32_dpp v143, v143, v143 quad_perm:[1,0,3,2] row_mask:0xf bank_mask:0xf bound_ctrl:1
	ds_read_b128 v[72:75], v124 offset:12544
	v_add_f32_dpp v142, v142, v142 quad_perm:[2,3,0,1] row_mask:0xf bank_mask:0xf bound_ctrl:1
	v_add_f32_dpp v143, v143, v143 quad_perm:[2,3,0,1] row_mask:0xf bank_mask:0xf bound_ctrl:1
	ds_read_b128 v[68:71], v124 offset:12800
	v_add_f32_dpp v142, v142, v142 row_half_mirror row_mask:0xf bank_mask:0xf bound_ctrl:1
	v_add_f32_dpp v143, v143, v143 row_half_mirror row_mask:0xf bank_mask:0xf bound_ctrl:1
	ds_read_b128 v[56:59], v124 offset:12816
	ds_read_b32 v0, v135 offset:13568
	ds_read_b128 v[64:67], v124 offset:13056
	ds_read_b128 v[60:63], v124 offset:13072
	ds_read_b128 v[48:51], v124 offset:12288
	ds_read_b128 v[40:43], v124 offset:12304
	v_pk_mul_f32 v[182:183], v[182:183], v[142:143] op_sel_hi:[1,0]
	v_pk_mul_f32 v[184:185], v[184:185], v[142:143] op_sel_hi:[1,0]
	s_mov_b32 vcc_lo, 0x40404040
	v_pk_mul_f32 v[186:187], v[186:187], v[142:143] op_sel_hi:[1,0]
	v_pk_mul_f32 v[188:189], v[188:189], v[142:143] op_sel_hi:[1,0]
	s_mov_b32 vcc_hi, 0x40404040
	v_pk_fma_f32 v[190:191], v[190:191], v[160:161], v[182:183] op_sel_hi:[1,0,1] neg_lo:[0,0,1] neg_hi:[0,0,1]
	v_pk_fma_f32 v[192:193], v[192:193], v[160:161], v[184:185] op_sel_hi:[1,0,1] neg_lo:[0,0,1] neg_hi:[0,0,1]
	v_cndmask_b32_e32 v134, v134, v143, vcc
	v_pk_fma_f32 v[194:195], v[194:195], v[160:161], v[186:187] op_sel_hi:[1,0,1] neg_lo:[0,0,1] neg_hi:[0,0,1]
	v_pk_fma_f32 v[196:197], v[196:197], v[160:161], v[188:189] op_sel_hi:[1,0,1] neg_lo:[0,0,1] neg_hi:[0,0,1]
	ds_read_b128 v[52:55], v124 offset:13328
	ds_read_b128 v[44:47], v124 offset:13312
	v_pk_fma_f32 v[36:37], v[36:37], v[144:145], v[190:191]
	v_pk_fma_f32 v[38:39], v[38:39], v[146:147], v[192:193]
	v_pk_fma_f32 v[32:33], v[32:33], v[148:149], v[194:195]
	v_pk_fma_f32 v[34:35], v[34:35], v[150:151], v[196:197]
	s_waitcnt lgkmcnt(2)
	v_pk_mul_f32 v[76:77], v[32:33], v[76:77]
	v_pk_mul_f32 v[202:203], v[32:33], v[202:203]
	v_pk_mul_f32 v[78:79], v[34:35], v[78:79]
	v_pk_mul_f32 v[204:205], v[34:35], v[204:205]
	v_pk_fma_f32 v[72:73], v[36:37], v[72:73], v[76:77]
	v_pk_fma_f32 v[198:199], v[36:37], v[198:199], v[202:203]
	v_pk_fma_f32 v[74:75], v[38:39], v[74:75], v[78:79]
	v_pk_fma_f32 v[200:201], v[38:39], v[200:201], v[204:205]
	v_pk_add_f32 v[72:73], v[72:73], v[74:75]
	v_pk_add_f32 v[198:199], v[198:199], v[200:201]
	v_add_f32_e32 v142, v72, v73
	v_add_f32_e32 v143, v198, v199
	ds_read_b128 v[156:159], v124 offset:14096
	v_add_f32_dpp v142, v142, v142 quad_perm:[1,0,3,2] row_mask:0xf bank_mask:0xf bound_ctrl:1
	v_add_f32_dpp v143, v143, v143 quad_perm:[1,0,3,2] row_mask:0xf bank_mask:0xf bound_ctrl:1
	ds_read_b128 v[152:155], v124 offset:14080
	v_add_f32_dpp v142, v142, v142 quad_perm:[2,3,0,1] row_mask:0xf bank_mask:0xf bound_ctrl:1
	v_add_f32_dpp v143, v143, v143 quad_perm:[2,3,0,1] row_mask:0xf bank_mask:0xf bound_ctrl:1
	ds_read_b128 v[182:185], v124 offset:14336
	v_add_f32_dpp v142, v142, v142 row_half_mirror row_mask:0xf bank_mask:0xf bound_ctrl:1
	v_add_f32_dpp v143, v143, v143 row_half_mirror row_mask:0xf bank_mask:0xf bound_ctrl:1
	ds_read_b128 v[186:189], v124 offset:14352
	ds_read_b32 v160, v135 offset:15104
	ds_read_b128 v[190:193], v124 offset:14592
	ds_read_b128 v[194:197], v124 offset:14608
	ds_read_b128 v[144:147], v124 offset:13824
	ds_read_b128 v[148:151], v124 offset:13840
	v_pk_mul_f32 v[68:69], v[68:69], v[142:143] op_sel_hi:[1,0]
	v_pk_mul_f32 v[70:71], v[70:71], v[142:143] op_sel_hi:[1,0]
	s_mov_b32 vcc_lo, 0x80808080
	v_pk_mul_f32 v[56:57], v[56:57], v[142:143] op_sel_hi:[1,0]
	v_pk_mul_f32 v[58:59], v[58:59], v[142:143] op_sel_hi:[1,0]
	s_mov_b32 vcc_hi, 0x80808080
	v_pk_fma_f32 v[64:65], v[64:65], v[0:1], v[68:69] op_sel_hi:[1,0,1] neg_lo:[0,0,1] neg_hi:[0,0,1]
	v_pk_fma_f32 v[66:67], v[66:67], v[0:1], v[70:71] op_sel_hi:[1,0,1] neg_lo:[0,0,1] neg_hi:[0,0,1]
	v_cndmask_b32_e32 v134, v134, v143, vcc
	v_pk_fma_f32 v[60:61], v[60:61], v[0:1], v[56:57] op_sel_hi:[1,0,1] neg_lo:[0,0,1] neg_hi:[0,0,1]
	v_pk_fma_f32 v[62:63], v[62:63], v[0:1], v[58:59] op_sel_hi:[1,0,1] neg_lo:[0,0,1] neg_hi:[0,0,1]
	ds_read_b128 v[202:205], v124 offset:14864
	ds_read_b128 v[198:201], v124 offset:14848
	v_pk_fma_f32 v[36:37], v[36:37], v[48:49], v[64:65]
	v_pk_fma_f32 v[38:39], v[38:39], v[50:51], v[66:67]
	v_pk_fma_f32 v[32:33], v[32:33], v[40:41], v[60:61]
	v_pk_fma_f32 v[34:35], v[34:35], v[42:43], v[62:63]
	s_waitcnt lgkmcnt(2)
	v_pk_mul_f32 v[156:157], v[32:33], v[156:157]
	v_pk_mul_f32 v[52:53], v[32:33], v[52:53]
	v_pk_mul_f32 v[158:159], v[34:35], v[158:159]
	v_pk_mul_f32 v[54:55], v[34:35], v[54:55]
	v_pk_fma_f32 v[152:153], v[36:37], v[152:153], v[156:157]
	v_pk_fma_f32 v[44:45], v[36:37], v[44:45], v[52:53]
	v_pk_fma_f32 v[154:155], v[38:39], v[154:155], v[158:159]
	v_pk_fma_f32 v[46:47], v[38:39], v[46:47], v[54:55]
	v_pk_add_f32 v[152:153], v[152:153], v[154:155]
	v_pk_add_f32 v[44:45], v[44:45], v[46:47]
	v_add_f32_e32 v142, v152, v153
	v_add_f32_e32 v143, v44, v45
	ds_read_b128 v[76:79], v124 offset:15632
	v_add_f32_dpp v142, v142, v142 quad_perm:[1,0,3,2] row_mask:0xf bank_mask:0xf bound_ctrl:1
	v_add_f32_dpp v143, v143, v143 quad_perm:[1,0,3,2] row_mask:0xf bank_mask:0xf bound_ctrl:1
	ds_read_b128 v[72:75], v124 offset:15616
	v_add_f32_dpp v142, v142, v142 quad_perm:[2,3,0,1] row_mask:0xf bank_mask:0xf bound_ctrl:1
	v_add_f32_dpp v143, v143, v143 quad_perm:[2,3,0,1] row_mask:0xf bank_mask:0xf bound_ctrl:1
	ds_read_b128 v[68:71], v124 offset:15872
	v_add_f32_dpp v142, v142, v142 row_half_mirror row_mask:0xf bank_mask:0xf bound_ctrl:1
	v_add_f32_dpp v143, v143, v143 row_half_mirror row_mask:0xf bank_mask:0xf bound_ctrl:1
	ds_read_b128 v[56:59], v124 offset:15888
	ds_read_b32 v0, v135 offset:16640
	ds_read_b128 v[64:67], v124 offset:16128
	ds_read_b128 v[60:63], v124 offset:16144
	ds_read_b128 v[48:51], v124 offset:15360
	ds_read_b128 v[40:43], v124 offset:15376
	v_pk_mul_f32 v[182:183], v[182:183], v[142:143] op_sel_hi:[1,0]
	v_pk_mul_f32 v[184:185], v[184:185], v[142:143] op_sel_hi:[1,0]
	s_mov_b32 vcc_lo, 0x1010101
	v_pk_mul_f32 v[186:187], v[186:187], v[142:143] op_sel_hi:[1,0]
	v_pk_mul_f32 v[188:189], v[188:189], v[142:143] op_sel_hi:[1,0]
	s_mov_b32 vcc_hi, 0x1010101
	v_pk_fma_f32 v[190:191], v[190:191], v[160:161], v[182:183] op_sel_hi:[1,0,1] neg_lo:[0,0,1] neg_hi:[0,0,1]
	v_pk_fma_f32 v[192:193], v[192:193], v[160:161], v[184:185] op_sel_hi:[1,0,1] neg_lo:[0,0,1] neg_hi:[0,0,1]
	v_cndmask_b32_e32 v133, v133, v143, vcc
	v_pk_fma_f32 v[194:195], v[194:195], v[160:161], v[186:187] op_sel_hi:[1,0,1] neg_lo:[0,0,1] neg_hi:[0,0,1]
	v_pk_fma_f32 v[196:197], v[196:197], v[160:161], v[188:189] op_sel_hi:[1,0,1] neg_lo:[0,0,1] neg_hi:[0,0,1]
	ds_read_b128 v[52:55], v124 offset:16400
	ds_read_b128 v[44:47], v124 offset:16384
	v_pk_fma_f32 v[36:37], v[36:37], v[144:145], v[190:191]
	v_pk_fma_f32 v[38:39], v[38:39], v[146:147], v[192:193]
	v_pk_fma_f32 v[32:33], v[32:33], v[148:149], v[194:195]
	v_pk_fma_f32 v[34:35], v[34:35], v[150:151], v[196:197]
	s_waitcnt lgkmcnt(2)
	v_pk_mul_f32 v[76:77], v[32:33], v[76:77]
	v_pk_mul_f32 v[202:203], v[32:33], v[202:203]
	v_pk_mul_f32 v[78:79], v[34:35], v[78:79]
	v_pk_mul_f32 v[204:205], v[34:35], v[204:205]
	v_pk_fma_f32 v[72:73], v[36:37], v[72:73], v[76:77]
	v_pk_fma_f32 v[198:199], v[36:37], v[198:199], v[202:203]
	v_pk_fma_f32 v[74:75], v[38:39], v[74:75], v[78:79]
	v_pk_fma_f32 v[200:201], v[38:39], v[200:201], v[204:205]
	v_pk_add_f32 v[72:73], v[72:73], v[74:75]
	v_pk_add_f32 v[198:199], v[198:199], v[200:201]
	v_add_f32_e32 v142, v72, v73
	v_add_f32_e32 v143, v198, v199
	ds_read_b128 v[156:159], v124 offset:17168
	v_add_f32_dpp v142, v142, v142 quad_perm:[1,0,3,2] row_mask:0xf bank_mask:0xf bound_ctrl:1
	v_add_f32_dpp v143, v143, v143 quad_perm:[1,0,3,2] row_mask:0xf bank_mask:0xf bound_ctrl:1
	ds_read_b128 v[152:155], v124 offset:17152
	v_add_f32_dpp v142, v142, v142 quad_perm:[2,3,0,1] row_mask:0xf bank_mask:0xf bound_ctrl:1
	v_add_f32_dpp v143, v143, v143 quad_perm:[2,3,0,1] row_mask:0xf bank_mask:0xf bound_ctrl:1
	ds_read_b128 v[182:185], v124 offset:17408
	v_add_f32_dpp v142, v142, v142 row_half_mirror row_mask:0xf bank_mask:0xf bound_ctrl:1
	v_add_f32_dpp v143, v143, v143 row_half_mirror row_mask:0xf bank_mask:0xf bound_ctrl:1
	ds_read_b128 v[186:189], v124 offset:17424
	ds_read_b32 v160, v135 offset:18176
	ds_read_b128 v[190:193], v124 offset:17664
	ds_read_b128 v[194:197], v124 offset:17680
	ds_read_b128 v[144:147], v124 offset:16896
	ds_read_b128 v[148:151], v124 offset:16912
	v_pk_mul_f32 v[68:69], v[68:69], v[142:143] op_sel_hi:[1,0]
	v_pk_mul_f32 v[70:71], v[70:71], v[142:143] op_sel_hi:[1,0]
	s_mov_b32 vcc_lo, 0x2020202
	v_pk_mul_f32 v[56:57], v[56:57], v[142:143] op_sel_hi:[1,0]
	v_pk_mul_f32 v[58:59], v[58:59], v[142:143] op_sel_hi:[1,0]
	s_mov_b32 vcc_hi, 0x2020202
	v_pk_fma_f32 v[64:65], v[64:65], v[0:1], v[68:69] op_sel_hi:[1,0,1] neg_lo:[0,0,1] neg_hi:[0,0,1]
	v_pk_fma_f32 v[66:67], v[66:67], v[0:1], v[70:71] op_sel_hi:[1,0,1] neg_lo:[0,0,1] neg_hi:[0,0,1]
	v_cndmask_b32_e32 v133, v133, v143, vcc
	v_pk_fma_f32 v[60:61], v[60:61], v[0:1], v[56:57] op_sel_hi:[1,0,1] neg_lo:[0,0,1] neg_hi:[0,0,1]
	v_pk_fma_f32 v[62:63], v[62:63], v[0:1], v[58:59] op_sel_hi:[1,0,1] neg_lo:[0,0,1] neg_hi:[0,0,1]
	ds_read_b128 v[202:205], v124 offset:17936
	ds_read_b128 v[198:201], v124 offset:17920
	v_pk_fma_f32 v[36:37], v[36:37], v[48:49], v[64:65]
	v_pk_fma_f32 v[38:39], v[38:39], v[50:51], v[66:67]
	v_pk_fma_f32 v[32:33], v[32:33], v[40:41], v[60:61]
	v_pk_fma_f32 v[34:35], v[34:35], v[42:43], v[62:63]
	s_waitcnt lgkmcnt(2)
	v_pk_mul_f32 v[156:157], v[32:33], v[156:157]
	v_pk_mul_f32 v[52:53], v[32:33], v[52:53]
	v_pk_mul_f32 v[158:159], v[34:35], v[158:159]
	v_pk_mul_f32 v[54:55], v[34:35], v[54:55]
	v_pk_fma_f32 v[152:153], v[36:37], v[152:153], v[156:157]
	v_pk_fma_f32 v[44:45], v[36:37], v[44:45], v[52:53]
	v_pk_fma_f32 v[154:155], v[38:39], v[154:155], v[158:159]
	v_pk_fma_f32 v[46:47], v[38:39], v[46:47], v[54:55]
	v_pk_add_f32 v[152:153], v[152:153], v[154:155]
	v_pk_add_f32 v[44:45], v[44:45], v[46:47]
	v_add_f32_e32 v142, v152, v153
	v_add_f32_e32 v143, v44, v45
	ds_read_b128 v[76:79], v124 offset:18704
	v_add_f32_dpp v142, v142, v142 quad_perm:[1,0,3,2] row_mask:0xf bank_mask:0xf bound_ctrl:1
	v_add_f32_dpp v143, v143, v143 quad_perm:[1,0,3,2] row_mask:0xf bank_mask:0xf bound_ctrl:1
	ds_read_b128 v[72:75], v124 offset:18688
	v_add_f32_dpp v142, v142, v142 quad_perm:[2,3,0,1] row_mask:0xf bank_mask:0xf bound_ctrl:1
	v_add_f32_dpp v143, v143, v143 quad_perm:[2,3,0,1] row_mask:0xf bank_mask:0xf bound_ctrl:1
	ds_read_b128 v[68:71], v124 offset:18944
	v_add_f32_dpp v142, v142, v142 row_half_mirror row_mask:0xf bank_mask:0xf bound_ctrl:1
	v_add_f32_dpp v143, v143, v143 row_half_mirror row_mask:0xf bank_mask:0xf bound_ctrl:1
	ds_read_b128 v[56:59], v124 offset:18960
	ds_read_b32 v0, v135 offset:19712
	ds_read_b128 v[64:67], v124 offset:19200
	ds_read_b128 v[60:63], v124 offset:19216
	ds_read_b128 v[48:51], v124 offset:18432
	ds_read_b128 v[40:43], v124 offset:18448
	v_pk_mul_f32 v[182:183], v[182:183], v[142:143] op_sel_hi:[1,0]
	v_pk_mul_f32 v[184:185], v[184:185], v[142:143] op_sel_hi:[1,0]
	s_mov_b32 vcc_lo, 0x4040404
	v_pk_mul_f32 v[186:187], v[186:187], v[142:143] op_sel_hi:[1,0]
	v_pk_mul_f32 v[188:189], v[188:189], v[142:143] op_sel_hi:[1,0]
	s_mov_b32 vcc_hi, 0x4040404
	v_pk_fma_f32 v[190:191], v[190:191], v[160:161], v[182:183] op_sel_hi:[1,0,1] neg_lo:[0,0,1] neg_hi:[0,0,1]
	v_pk_fma_f32 v[192:193], v[192:193], v[160:161], v[184:185] op_sel_hi:[1,0,1] neg_lo:[0,0,1] neg_hi:[0,0,1]
	v_cndmask_b32_e32 v133, v133, v143, vcc
	v_pk_fma_f32 v[194:195], v[194:195], v[160:161], v[186:187] op_sel_hi:[1,0,1] neg_lo:[0,0,1] neg_hi:[0,0,1]
	v_pk_fma_f32 v[196:197], v[196:197], v[160:161], v[188:189] op_sel_hi:[1,0,1] neg_lo:[0,0,1] neg_hi:[0,0,1]
	ds_read_b128 v[52:55], v124 offset:19472
	ds_read_b128 v[44:47], v124 offset:19456
	v_pk_fma_f32 v[36:37], v[36:37], v[144:145], v[190:191]
	v_pk_fma_f32 v[38:39], v[38:39], v[146:147], v[192:193]
	v_pk_fma_f32 v[32:33], v[32:33], v[148:149], v[194:195]
	v_pk_fma_f32 v[34:35], v[34:35], v[150:151], v[196:197]
	s_waitcnt lgkmcnt(2)
	v_pk_mul_f32 v[76:77], v[32:33], v[76:77]
	v_pk_mul_f32 v[202:203], v[32:33], v[202:203]
	v_pk_mul_f32 v[78:79], v[34:35], v[78:79]
	v_pk_mul_f32 v[204:205], v[34:35], v[204:205]
	v_pk_fma_f32 v[72:73], v[36:37], v[72:73], v[76:77]
	v_pk_fma_f32 v[198:199], v[36:37], v[198:199], v[202:203]
	v_pk_fma_f32 v[74:75], v[38:39], v[74:75], v[78:79]
	v_pk_fma_f32 v[200:201], v[38:39], v[200:201], v[204:205]
	v_pk_add_f32 v[72:73], v[72:73], v[74:75]
	v_pk_add_f32 v[198:199], v[198:199], v[200:201]
	v_add_f32_e32 v142, v72, v73
	v_add_f32_e32 v143, v198, v199
	ds_read_b128 v[156:159], v124 offset:20240
	v_add_f32_dpp v142, v142, v142 quad_perm:[1,0,3,2] row_mask:0xf bank_mask:0xf bound_ctrl:1
	v_add_f32_dpp v143, v143, v143 quad_perm:[1,0,3,2] row_mask:0xf bank_mask:0xf bound_ctrl:1
	ds_read_b128 v[152:155], v124 offset:20224
	v_add_f32_dpp v142, v142, v142 quad_perm:[2,3,0,1] row_mask:0xf bank_mask:0xf bound_ctrl:1
	v_add_f32_dpp v143, v143, v143 quad_perm:[2,3,0,1] row_mask:0xf bank_mask:0xf bound_ctrl:1
	ds_read_b128 v[182:185], v124 offset:20480
	v_add_f32_dpp v142, v142, v142 row_half_mirror row_mask:0xf bank_mask:0xf bound_ctrl:1
	v_add_f32_dpp v143, v143, v143 row_half_mirror row_mask:0xf bank_mask:0xf bound_ctrl:1
	ds_read_b128 v[186:189], v124 offset:20496
	ds_read_b32 v160, v135 offset:21248
	ds_read_b128 v[190:193], v124 offset:20736
	ds_read_b128 v[194:197], v124 offset:20752
	ds_read_b128 v[144:147], v124 offset:19968
	ds_read_b128 v[148:151], v124 offset:19984
	v_pk_mul_f32 v[68:69], v[68:69], v[142:143] op_sel_hi:[1,0]
	v_pk_mul_f32 v[70:71], v[70:71], v[142:143] op_sel_hi:[1,0]
	s_mov_b32 vcc_lo, 0x8080808
	v_pk_mul_f32 v[56:57], v[56:57], v[142:143] op_sel_hi:[1,0]
	v_pk_mul_f32 v[58:59], v[58:59], v[142:143] op_sel_hi:[1,0]
	s_mov_b32 vcc_hi, 0x8080808
	v_pk_fma_f32 v[64:65], v[64:65], v[0:1], v[68:69] op_sel_hi:[1,0,1] neg_lo:[0,0,1] neg_hi:[0,0,1]
	v_pk_fma_f32 v[66:67], v[66:67], v[0:1], v[70:71] op_sel_hi:[1,0,1] neg_lo:[0,0,1] neg_hi:[0,0,1]
	v_cndmask_b32_e32 v133, v133, v143, vcc
	v_pk_fma_f32 v[60:61], v[60:61], v[0:1], v[56:57] op_sel_hi:[1,0,1] neg_lo:[0,0,1] neg_hi:[0,0,1]
	v_pk_fma_f32 v[62:63], v[62:63], v[0:1], v[58:59] op_sel_hi:[1,0,1] neg_lo:[0,0,1] neg_hi:[0,0,1]
	ds_read_b128 v[202:205], v124 offset:21008
	ds_read_b128 v[198:201], v124 offset:20992
	v_pk_fma_f32 v[36:37], v[36:37], v[48:49], v[64:65]
	v_pk_fma_f32 v[38:39], v[38:39], v[50:51], v[66:67]
	v_pk_fma_f32 v[32:33], v[32:33], v[40:41], v[60:61]
	v_pk_fma_f32 v[34:35], v[34:35], v[42:43], v[62:63]
	s_waitcnt lgkmcnt(2)
	v_pk_mul_f32 v[156:157], v[32:33], v[156:157]
	v_pk_mul_f32 v[52:53], v[32:33], v[52:53]
	v_pk_mul_f32 v[158:159], v[34:35], v[158:159]
	v_pk_mul_f32 v[54:55], v[34:35], v[54:55]
	v_pk_fma_f32 v[152:153], v[36:37], v[152:153], v[156:157]
	v_pk_fma_f32 v[44:45], v[36:37], v[44:45], v[52:53]
	v_pk_fma_f32 v[154:155], v[38:39], v[154:155], v[158:159]
	v_pk_fma_f32 v[46:47], v[38:39], v[46:47], v[54:55]
	v_pk_add_f32 v[152:153], v[152:153], v[154:155]
	v_pk_add_f32 v[44:45], v[44:45], v[46:47]
	v_add_f32_e32 v142, v152, v153
	v_add_f32_e32 v143, v44, v45
	ds_read_b128 v[76:79], v124 offset:21776
	v_add_f32_dpp v142, v142, v142 quad_perm:[1,0,3,2] row_mask:0xf bank_mask:0xf bound_ctrl:1
	v_add_f32_dpp v143, v143, v143 quad_perm:[1,0,3,2] row_mask:0xf bank_mask:0xf bound_ctrl:1
	ds_read_b128 v[72:75], v124 offset:21760
	v_add_f32_dpp v142, v142, v142 quad_perm:[2,3,0,1] row_mask:0xf bank_mask:0xf bound_ctrl:1
	v_add_f32_dpp v143, v143, v143 quad_perm:[2,3,0,1] row_mask:0xf bank_mask:0xf bound_ctrl:1
	ds_read_b128 v[68:71], v124 offset:22016
	v_add_f32_dpp v142, v142, v142 row_half_mirror row_mask:0xf bank_mask:0xf bound_ctrl:1
	v_add_f32_dpp v143, v143, v143 row_half_mirror row_mask:0xf bank_mask:0xf bound_ctrl:1
	ds_read_b128 v[56:59], v124 offset:22032
	ds_read_b32 v0, v135 offset:22784
	ds_read_b128 v[64:67], v124 offset:22272
	ds_read_b128 v[60:63], v124 offset:22288
	ds_read_b128 v[48:51], v124 offset:21504
	ds_read_b128 v[40:43], v124 offset:21520
	v_pk_mul_f32 v[182:183], v[182:183], v[142:143] op_sel_hi:[1,0]
	v_pk_mul_f32 v[184:185], v[184:185], v[142:143] op_sel_hi:[1,0]
	s_mov_b32 vcc_lo, 0x10101010
	v_pk_mul_f32 v[186:187], v[186:187], v[142:143] op_sel_hi:[1,0]
	v_pk_mul_f32 v[188:189], v[188:189], v[142:143] op_sel_hi:[1,0]
	s_mov_b32 vcc_hi, 0x10101010
	v_pk_fma_f32 v[190:191], v[190:191], v[160:161], v[182:183] op_sel_hi:[1,0,1] neg_lo:[0,0,1] neg_hi:[0,0,1]
	v_pk_fma_f32 v[192:193], v[192:193], v[160:161], v[184:185] op_sel_hi:[1,0,1] neg_lo:[0,0,1] neg_hi:[0,0,1]
	v_cndmask_b32_e32 v133, v133, v143, vcc
	v_pk_fma_f32 v[194:195], v[194:195], v[160:161], v[186:187] op_sel_hi:[1,0,1] neg_lo:[0,0,1] neg_hi:[0,0,1]
	v_pk_fma_f32 v[196:197], v[196:197], v[160:161], v[188:189] op_sel_hi:[1,0,1] neg_lo:[0,0,1] neg_hi:[0,0,1]
	ds_read_b128 v[52:55], v124 offset:22544
	ds_read_b128 v[44:47], v124 offset:22528
	v_pk_fma_f32 v[36:37], v[36:37], v[144:145], v[190:191]
	v_pk_fma_f32 v[38:39], v[38:39], v[146:147], v[192:193]
	v_pk_fma_f32 v[32:33], v[32:33], v[148:149], v[194:195]
	v_pk_fma_f32 v[34:35], v[34:35], v[150:151], v[196:197]
	s_waitcnt lgkmcnt(2)
	v_pk_mul_f32 v[76:77], v[32:33], v[76:77]
	v_pk_mul_f32 v[202:203], v[32:33], v[202:203]
	v_pk_mul_f32 v[78:79], v[34:35], v[78:79]
	v_pk_mul_f32 v[204:205], v[34:35], v[204:205]
	v_pk_fma_f32 v[72:73], v[36:37], v[72:73], v[76:77]
	v_pk_fma_f32 v[198:199], v[36:37], v[198:199], v[202:203]
	v_pk_fma_f32 v[74:75], v[38:39], v[74:75], v[78:79]
	v_pk_fma_f32 v[200:201], v[38:39], v[200:201], v[204:205]
	v_pk_add_f32 v[72:73], v[72:73], v[74:75]
	v_pk_add_f32 v[198:199], v[198:199], v[200:201]
	v_add_f32_e32 v142, v72, v73
	v_add_f32_e32 v143, v198, v199
	ds_read_b128 v[156:159], v124 offset:23312
	v_add_f32_dpp v142, v142, v142 quad_perm:[1,0,3,2] row_mask:0xf bank_mask:0xf bound_ctrl:1
	v_add_f32_dpp v143, v143, v143 quad_perm:[1,0,3,2] row_mask:0xf bank_mask:0xf bound_ctrl:1
	ds_read_b128 v[152:155], v124 offset:23296
	v_add_f32_dpp v142, v142, v142 quad_perm:[2,3,0,1] row_mask:0xf bank_mask:0xf bound_ctrl:1
	v_add_f32_dpp v143, v143, v143 quad_perm:[2,3,0,1] row_mask:0xf bank_mask:0xf bound_ctrl:1
	ds_read_b128 v[182:185], v124 offset:23552
	v_add_f32_dpp v142, v142, v142 row_half_mirror row_mask:0xf bank_mask:0xf bound_ctrl:1
	v_add_f32_dpp v143, v143, v143 row_half_mirror row_mask:0xf bank_mask:0xf bound_ctrl:1
	ds_read_b128 v[186:189], v124 offset:23568
	ds_read_b32 v160, v135 offset:24320
	ds_read_b128 v[190:193], v124 offset:23808
	ds_read_b128 v[194:197], v124 offset:23824
	ds_read_b128 v[144:147], v124 offset:23040
	ds_read_b128 v[148:151], v124 offset:23056
	v_pk_mul_f32 v[68:69], v[68:69], v[142:143] op_sel_hi:[1,0]
	v_pk_mul_f32 v[70:71], v[70:71], v[142:143] op_sel_hi:[1,0]
	s_mov_b32 vcc_lo, 0x20202020
	v_pk_mul_f32 v[56:57], v[56:57], v[142:143] op_sel_hi:[1,0]
	v_pk_mul_f32 v[58:59], v[58:59], v[142:143] op_sel_hi:[1,0]
	s_mov_b32 vcc_hi, 0x20202020
	v_pk_fma_f32 v[64:65], v[64:65], v[0:1], v[68:69] op_sel_hi:[1,0,1] neg_lo:[0,0,1] neg_hi:[0,0,1]
	v_pk_fma_f32 v[66:67], v[66:67], v[0:1], v[70:71] op_sel_hi:[1,0,1] neg_lo:[0,0,1] neg_hi:[0,0,1]
	v_cndmask_b32_e32 v133, v133, v143, vcc
	v_pk_fma_f32 v[60:61], v[60:61], v[0:1], v[56:57] op_sel_hi:[1,0,1] neg_lo:[0,0,1] neg_hi:[0,0,1]
	v_pk_fma_f32 v[62:63], v[62:63], v[0:1], v[58:59] op_sel_hi:[1,0,1] neg_lo:[0,0,1] neg_hi:[0,0,1]
	ds_read_b128 v[202:205], v124 offset:24080
	ds_read_b128 v[198:201], v124 offset:24064
	v_pk_fma_f32 v[36:37], v[36:37], v[48:49], v[64:65]
	v_pk_fma_f32 v[38:39], v[38:39], v[50:51], v[66:67]
	v_pk_fma_f32 v[32:33], v[32:33], v[40:41], v[60:61]
	v_pk_fma_f32 v[34:35], v[34:35], v[42:43], v[62:63]
	s_waitcnt lgkmcnt(2)
	v_pk_mul_f32 v[156:157], v[32:33], v[156:157]
	v_pk_mul_f32 v[52:53], v[32:33], v[52:53]
	v_pk_mul_f32 v[158:159], v[34:35], v[158:159]
	v_pk_mul_f32 v[54:55], v[34:35], v[54:55]
	v_pk_fma_f32 v[152:153], v[36:37], v[152:153], v[156:157]
	v_pk_fma_f32 v[44:45], v[36:37], v[44:45], v[52:53]
	v_pk_fma_f32 v[154:155], v[38:39], v[154:155], v[158:159]
	v_pk_fma_f32 v[46:47], v[38:39], v[46:47], v[54:55]
	v_pk_add_f32 v[152:153], v[152:153], v[154:155]
	v_pk_add_f32 v[44:45], v[44:45], v[46:47]
	v_add_f32_e32 v142, v152, v153
	v_add_f32_e32 v143, v44, v45
	ds_read_b128 v[76:79], v124 offset:24848
	v_add_f32_dpp v142, v142, v142 quad_perm:[1,0,3,2] row_mask:0xf bank_mask:0xf bound_ctrl:1
	v_add_f32_dpp v143, v143, v143 quad_perm:[1,0,3,2] row_mask:0xf bank_mask:0xf bound_ctrl:1
	ds_read_b128 v[72:75], v124 offset:24832
	v_add_f32_dpp v142, v142, v142 quad_perm:[2,3,0,1] row_mask:0xf bank_mask:0xf bound_ctrl:1
	v_add_f32_dpp v143, v143, v143 quad_perm:[2,3,0,1] row_mask:0xf bank_mask:0xf bound_ctrl:1
	ds_read_b128 v[68:71], v124 offset:25088
	v_add_f32_dpp v142, v142, v142 row_half_mirror row_mask:0xf bank_mask:0xf bound_ctrl:1
	v_add_f32_dpp v143, v143, v143 row_half_mirror row_mask:0xf bank_mask:0xf bound_ctrl:1
	ds_read_b128 v[56:59], v124 offset:25104
	ds_read_b32 v0, v135 offset:25856
	ds_read_b128 v[64:67], v124 offset:25344
	ds_read_b128 v[60:63], v124 offset:25360
	ds_read_b128 v[48:51], v124 offset:24576
	ds_read_b128 v[40:43], v124 offset:24592
	v_pk_mul_f32 v[182:183], v[182:183], v[142:143] op_sel_hi:[1,0]
	v_pk_mul_f32 v[184:185], v[184:185], v[142:143] op_sel_hi:[1,0]
	s_mov_b32 vcc_lo, 0x40404040
	v_pk_mul_f32 v[186:187], v[186:187], v[142:143] op_sel_hi:[1,0]
	v_pk_mul_f32 v[188:189], v[188:189], v[142:143] op_sel_hi:[1,0]
	s_mov_b32 vcc_hi, 0x40404040
	v_pk_fma_f32 v[190:191], v[190:191], v[160:161], v[182:183] op_sel_hi:[1,0,1] neg_lo:[0,0,1] neg_hi:[0,0,1]
	v_pk_fma_f32 v[192:193], v[192:193], v[160:161], v[184:185] op_sel_hi:[1,0,1] neg_lo:[0,0,1] neg_hi:[0,0,1]
	v_cndmask_b32_e32 v133, v133, v143, vcc
	v_pk_fma_f32 v[194:195], v[194:195], v[160:161], v[186:187] op_sel_hi:[1,0,1] neg_lo:[0,0,1] neg_hi:[0,0,1]
	v_pk_fma_f32 v[196:197], v[196:197], v[160:161], v[188:189] op_sel_hi:[1,0,1] neg_lo:[0,0,1] neg_hi:[0,0,1]
	ds_read_b128 v[52:55], v124 offset:25616
	ds_read_b128 v[44:47], v124 offset:25600
	v_pk_fma_f32 v[36:37], v[36:37], v[144:145], v[190:191]
	v_pk_fma_f32 v[38:39], v[38:39], v[146:147], v[192:193]
	v_pk_fma_f32 v[32:33], v[32:33], v[148:149], v[194:195]
	v_pk_fma_f32 v[34:35], v[34:35], v[150:151], v[196:197]
	s_waitcnt lgkmcnt(2)
	v_pk_mul_f32 v[76:77], v[32:33], v[76:77]
	v_pk_mul_f32 v[202:203], v[32:33], v[202:203]
	v_pk_mul_f32 v[78:79], v[34:35], v[78:79]
	v_pk_mul_f32 v[204:205], v[34:35], v[204:205]
	v_pk_fma_f32 v[72:73], v[36:37], v[72:73], v[76:77]
	v_pk_fma_f32 v[198:199], v[36:37], v[198:199], v[202:203]
	v_pk_fma_f32 v[74:75], v[38:39], v[74:75], v[78:79]
	v_pk_fma_f32 v[200:201], v[38:39], v[200:201], v[204:205]
	v_pk_add_f32 v[72:73], v[72:73], v[74:75]
	v_pk_add_f32 v[198:199], v[198:199], v[200:201]
	v_add_f32_e32 v142, v72, v73
	v_add_f32_e32 v143, v198, v199
	ds_read_b128 v[156:159], v124 offset:26384
	v_add_f32_dpp v142, v142, v142 quad_perm:[1,0,3,2] row_mask:0xf bank_mask:0xf bound_ctrl:1
	v_add_f32_dpp v143, v143, v143 quad_perm:[1,0,3,2] row_mask:0xf bank_mask:0xf bound_ctrl:1
	ds_read_b128 v[152:155], v124 offset:26368
	v_add_f32_dpp v142, v142, v142 quad_perm:[2,3,0,1] row_mask:0xf bank_mask:0xf bound_ctrl:1
	v_add_f32_dpp v143, v143, v143 quad_perm:[2,3,0,1] row_mask:0xf bank_mask:0xf bound_ctrl:1
	ds_read_b128 v[182:185], v124 offset:26624
	v_add_f32_dpp v142, v142, v142 row_half_mirror row_mask:0xf bank_mask:0xf bound_ctrl:1
	v_add_f32_dpp v143, v143, v143 row_half_mirror row_mask:0xf bank_mask:0xf bound_ctrl:1
	ds_read_b128 v[186:189], v124 offset:26640
	ds_read_b32 v160, v135 offset:27392
	ds_read_b128 v[190:193], v124 offset:26880
	ds_read_b128 v[194:197], v124 offset:26896
	ds_read_b128 v[144:147], v124 offset:26112
	ds_read_b128 v[148:151], v124 offset:26128
	v_pk_mul_f32 v[68:69], v[68:69], v[142:143] op_sel_hi:[1,0]
	v_pk_mul_f32 v[70:71], v[70:71], v[142:143] op_sel_hi:[1,0]
	s_mov_b32 vcc_lo, 0x80808080
	v_pk_mul_f32 v[56:57], v[56:57], v[142:143] op_sel_hi:[1,0]
	v_pk_mul_f32 v[58:59], v[58:59], v[142:143] op_sel_hi:[1,0]
	s_mov_b32 vcc_hi, 0x80808080
	v_pk_fma_f32 v[64:65], v[64:65], v[0:1], v[68:69] op_sel_hi:[1,0,1] neg_lo:[0,0,1] neg_hi:[0,0,1]
	v_pk_fma_f32 v[66:67], v[66:67], v[0:1], v[70:71] op_sel_hi:[1,0,1] neg_lo:[0,0,1] neg_hi:[0,0,1]
	v_cndmask_b32_e32 v133, v133, v143, vcc
	v_pk_fma_f32 v[60:61], v[60:61], v[0:1], v[56:57] op_sel_hi:[1,0,1] neg_lo:[0,0,1] neg_hi:[0,0,1]
	v_pk_fma_f32 v[62:63], v[62:63], v[0:1], v[58:59] op_sel_hi:[1,0,1] neg_lo:[0,0,1] neg_hi:[0,0,1]
	ds_read_b128 v[202:205], v124 offset:27152
	ds_read_b128 v[198:201], v124 offset:27136
	v_pk_fma_f32 v[36:37], v[36:37], v[48:49], v[64:65]
	v_pk_fma_f32 v[38:39], v[38:39], v[50:51], v[66:67]
	v_pk_fma_f32 v[32:33], v[32:33], v[40:41], v[60:61]
	v_pk_fma_f32 v[34:35], v[34:35], v[42:43], v[62:63]
	s_waitcnt lgkmcnt(2)
	v_pk_mul_f32 v[156:157], v[32:33], v[156:157]
	v_pk_mul_f32 v[52:53], v[32:33], v[52:53]
	v_pk_mul_f32 v[158:159], v[34:35], v[158:159]
	v_pk_mul_f32 v[54:55], v[34:35], v[54:55]
	v_pk_fma_f32 v[152:153], v[36:37], v[152:153], v[156:157]
	v_pk_fma_f32 v[44:45], v[36:37], v[44:45], v[52:53]
	v_pk_fma_f32 v[154:155], v[38:39], v[154:155], v[158:159]
	v_pk_fma_f32 v[46:47], v[38:39], v[46:47], v[54:55]
	v_pk_add_f32 v[152:153], v[152:153], v[154:155]
	v_pk_add_f32 v[44:45], v[44:45], v[46:47]
	v_add_f32_e32 v142, v152, v153
	v_add_f32_e32 v143, v44, v45
	ds_read_b128 v[76:79], v124 offset:27920
	v_add_f32_dpp v142, v142, v142 quad_perm:[1,0,3,2] row_mask:0xf bank_mask:0xf bound_ctrl:1
	v_add_f32_dpp v143, v143, v143 quad_perm:[1,0,3,2] row_mask:0xf bank_mask:0xf bound_ctrl:1
	ds_read_b128 v[72:75], v124 offset:27904
	v_add_f32_dpp v142, v142, v142 quad_perm:[2,3,0,1] row_mask:0xf bank_mask:0xf bound_ctrl:1
	v_add_f32_dpp v143, v143, v143 quad_perm:[2,3,0,1] row_mask:0xf bank_mask:0xf bound_ctrl:1
	ds_read_b128 v[68:71], v124 offset:28160
	v_add_f32_dpp v142, v142, v142 row_half_mirror row_mask:0xf bank_mask:0xf bound_ctrl:1
	v_add_f32_dpp v143, v143, v143 row_half_mirror row_mask:0xf bank_mask:0xf bound_ctrl:1
	ds_read_b128 v[56:59], v124 offset:28176
	ds_read_b32 v0, v135 offset:28928
	ds_read_b128 v[64:67], v124 offset:28416
	ds_read_b128 v[60:63], v124 offset:28432
	ds_read_b128 v[48:51], v124 offset:27648
	ds_read_b128 v[40:43], v124 offset:27664
	v_pk_mul_f32 v[182:183], v[182:183], v[142:143] op_sel_hi:[1,0]
	v_pk_mul_f32 v[184:185], v[184:185], v[142:143] op_sel_hi:[1,0]
	s_mov_b32 vcc_lo, 0x1010101
	v_pk_mul_f32 v[186:187], v[186:187], v[142:143] op_sel_hi:[1,0]
	v_pk_mul_f32 v[188:189], v[188:189], v[142:143] op_sel_hi:[1,0]
	s_mov_b32 vcc_hi, 0x1010101
	v_pk_fma_f32 v[190:191], v[190:191], v[160:161], v[182:183] op_sel_hi:[1,0,1] neg_lo:[0,0,1] neg_hi:[0,0,1]
	v_pk_fma_f32 v[192:193], v[192:193], v[160:161], v[184:185] op_sel_hi:[1,0,1] neg_lo:[0,0,1] neg_hi:[0,0,1]
	v_cndmask_b32_e32 v132, v132, v143, vcc
	v_pk_fma_f32 v[194:195], v[194:195], v[160:161], v[186:187] op_sel_hi:[1,0,1] neg_lo:[0,0,1] neg_hi:[0,0,1]
	v_pk_fma_f32 v[196:197], v[196:197], v[160:161], v[188:189] op_sel_hi:[1,0,1] neg_lo:[0,0,1] neg_hi:[0,0,1]
	ds_read_b128 v[52:55], v124 offset:28688
	ds_read_b128 v[44:47], v124 offset:28672
	v_pk_fma_f32 v[36:37], v[36:37], v[144:145], v[190:191]
	v_pk_fma_f32 v[38:39], v[38:39], v[146:147], v[192:193]
	v_pk_fma_f32 v[32:33], v[32:33], v[148:149], v[194:195]
	v_pk_fma_f32 v[34:35], v[34:35], v[150:151], v[196:197]
	s_waitcnt lgkmcnt(2)
	v_pk_mul_f32 v[76:77], v[32:33], v[76:77]
	v_pk_mul_f32 v[202:203], v[32:33], v[202:203]
	v_pk_mul_f32 v[78:79], v[34:35], v[78:79]
	v_pk_mul_f32 v[204:205], v[34:35], v[204:205]
	v_pk_fma_f32 v[72:73], v[36:37], v[72:73], v[76:77]
	v_pk_fma_f32 v[198:199], v[36:37], v[198:199], v[202:203]
	v_pk_fma_f32 v[74:75], v[38:39], v[74:75], v[78:79]
	v_pk_fma_f32 v[200:201], v[38:39], v[200:201], v[204:205]
	v_pk_add_f32 v[72:73], v[72:73], v[74:75]
	v_pk_add_f32 v[198:199], v[198:199], v[200:201]
	v_add_f32_e32 v142, v72, v73
	v_add_f32_e32 v143, v198, v199
	ds_read_b128 v[156:159], v124 offset:29456
	v_add_f32_dpp v142, v142, v142 quad_perm:[1,0,3,2] row_mask:0xf bank_mask:0xf bound_ctrl:1
	v_add_f32_dpp v143, v143, v143 quad_perm:[1,0,3,2] row_mask:0xf bank_mask:0xf bound_ctrl:1
	ds_read_b128 v[152:155], v124 offset:29440
	v_add_f32_dpp v142, v142, v142 quad_perm:[2,3,0,1] row_mask:0xf bank_mask:0xf bound_ctrl:1
	v_add_f32_dpp v143, v143, v143 quad_perm:[2,3,0,1] row_mask:0xf bank_mask:0xf bound_ctrl:1
	ds_read_b128 v[182:185], v124 offset:29696
	v_add_f32_dpp v142, v142, v142 row_half_mirror row_mask:0xf bank_mask:0xf bound_ctrl:1
	v_add_f32_dpp v143, v143, v143 row_half_mirror row_mask:0xf bank_mask:0xf bound_ctrl:1
	ds_read_b128 v[186:189], v124 offset:29712
	ds_read_b32 v160, v135 offset:30464
	ds_read_b128 v[190:193], v124 offset:29952
	ds_read_b128 v[194:197], v124 offset:29968
	ds_read_b128 v[144:147], v124 offset:29184
	ds_read_b128 v[148:151], v124 offset:29200
	v_pk_mul_f32 v[68:69], v[68:69], v[142:143] op_sel_hi:[1,0]
	v_pk_mul_f32 v[70:71], v[70:71], v[142:143] op_sel_hi:[1,0]
	s_mov_b32 vcc_lo, 0x2020202
	v_pk_mul_f32 v[56:57], v[56:57], v[142:143] op_sel_hi:[1,0]
	v_pk_mul_f32 v[58:59], v[58:59], v[142:143] op_sel_hi:[1,0]
	s_mov_b32 vcc_hi, 0x2020202
	v_pk_fma_f32 v[64:65], v[64:65], v[0:1], v[68:69] op_sel_hi:[1,0,1] neg_lo:[0,0,1] neg_hi:[0,0,1]
	v_pk_fma_f32 v[66:67], v[66:67], v[0:1], v[70:71] op_sel_hi:[1,0,1] neg_lo:[0,0,1] neg_hi:[0,0,1]
	v_cndmask_b32_e32 v132, v132, v143, vcc
	v_pk_fma_f32 v[60:61], v[60:61], v[0:1], v[56:57] op_sel_hi:[1,0,1] neg_lo:[0,0,1] neg_hi:[0,0,1]
	v_pk_fma_f32 v[62:63], v[62:63], v[0:1], v[58:59] op_sel_hi:[1,0,1] neg_lo:[0,0,1] neg_hi:[0,0,1]
	ds_read_b128 v[202:205], v124 offset:30224
	ds_read_b128 v[198:201], v124 offset:30208
	v_pk_fma_f32 v[36:37], v[36:37], v[48:49], v[64:65]
	v_pk_fma_f32 v[38:39], v[38:39], v[50:51], v[66:67]
	v_pk_fma_f32 v[32:33], v[32:33], v[40:41], v[60:61]
	v_pk_fma_f32 v[34:35], v[34:35], v[42:43], v[62:63]
	s_waitcnt lgkmcnt(2)
	v_pk_mul_f32 v[156:157], v[32:33], v[156:157]
	v_pk_mul_f32 v[52:53], v[32:33], v[52:53]
	v_pk_mul_f32 v[158:159], v[34:35], v[158:159]
	v_pk_mul_f32 v[54:55], v[34:35], v[54:55]
	v_pk_fma_f32 v[152:153], v[36:37], v[152:153], v[156:157]
	v_pk_fma_f32 v[44:45], v[36:37], v[44:45], v[52:53]
	v_pk_fma_f32 v[154:155], v[38:39], v[154:155], v[158:159]
	v_pk_fma_f32 v[46:47], v[38:39], v[46:47], v[54:55]
	v_pk_add_f32 v[152:153], v[152:153], v[154:155]
	v_pk_add_f32 v[44:45], v[44:45], v[46:47]
	v_add_f32_e32 v142, v152, v153
	v_add_f32_e32 v143, v44, v45
	ds_read_b128 v[76:79], v124 offset:30992
	v_add_f32_dpp v142, v142, v142 quad_perm:[1,0,3,2] row_mask:0xf bank_mask:0xf bound_ctrl:1
	v_add_f32_dpp v143, v143, v143 quad_perm:[1,0,3,2] row_mask:0xf bank_mask:0xf bound_ctrl:1
	ds_read_b128 v[72:75], v124 offset:30976
	v_add_f32_dpp v142, v142, v142 quad_perm:[2,3,0,1] row_mask:0xf bank_mask:0xf bound_ctrl:1
	v_add_f32_dpp v143, v143, v143 quad_perm:[2,3,0,1] row_mask:0xf bank_mask:0xf bound_ctrl:1
	ds_read_b128 v[68:71], v124 offset:31232
	v_add_f32_dpp v142, v142, v142 row_half_mirror row_mask:0xf bank_mask:0xf bound_ctrl:1
	v_add_f32_dpp v143, v143, v143 row_half_mirror row_mask:0xf bank_mask:0xf bound_ctrl:1
	ds_read_b128 v[56:59], v124 offset:31248
	ds_read_b32 v0, v135 offset:32000
	ds_read_b128 v[64:67], v124 offset:31488
	ds_read_b128 v[60:63], v124 offset:31504
	ds_read_b128 v[48:51], v124 offset:30720
	ds_read_b128 v[40:43], v124 offset:30736
	v_pk_mul_f32 v[182:183], v[182:183], v[142:143] op_sel_hi:[1,0]
	v_pk_mul_f32 v[184:185], v[184:185], v[142:143] op_sel_hi:[1,0]
	s_mov_b32 vcc_lo, 0x4040404
	v_pk_mul_f32 v[186:187], v[186:187], v[142:143] op_sel_hi:[1,0]
	v_pk_mul_f32 v[188:189], v[188:189], v[142:143] op_sel_hi:[1,0]
	s_mov_b32 vcc_hi, 0x4040404
	v_pk_fma_f32 v[190:191], v[190:191], v[160:161], v[182:183] op_sel_hi:[1,0,1] neg_lo:[0,0,1] neg_hi:[0,0,1]
	v_pk_fma_f32 v[192:193], v[192:193], v[160:161], v[184:185] op_sel_hi:[1,0,1] neg_lo:[0,0,1] neg_hi:[0,0,1]
	v_cndmask_b32_e32 v132, v132, v143, vcc
	v_pk_fma_f32 v[194:195], v[194:195], v[160:161], v[186:187] op_sel_hi:[1,0,1] neg_lo:[0,0,1] neg_hi:[0,0,1]
	v_pk_fma_f32 v[196:197], v[196:197], v[160:161], v[188:189] op_sel_hi:[1,0,1] neg_lo:[0,0,1] neg_hi:[0,0,1]
	ds_read_b128 v[52:55], v124 offset:31760
	ds_read_b128 v[44:47], v124 offset:31744
	v_pk_fma_f32 v[36:37], v[36:37], v[144:145], v[190:191]
	v_pk_fma_f32 v[38:39], v[38:39], v[146:147], v[192:193]
	v_pk_fma_f32 v[32:33], v[32:33], v[148:149], v[194:195]
	v_pk_fma_f32 v[34:35], v[34:35], v[150:151], v[196:197]
	s_waitcnt lgkmcnt(2)
	v_pk_mul_f32 v[76:77], v[32:33], v[76:77]
	v_pk_mul_f32 v[202:203], v[32:33], v[202:203]
	v_pk_mul_f32 v[78:79], v[34:35], v[78:79]
	v_pk_mul_f32 v[204:205], v[34:35], v[204:205]
	v_pk_fma_f32 v[72:73], v[36:37], v[72:73], v[76:77]
	v_pk_fma_f32 v[198:199], v[36:37], v[198:199], v[202:203]
	v_pk_fma_f32 v[74:75], v[38:39], v[74:75], v[78:79]
	v_pk_fma_f32 v[200:201], v[38:39], v[200:201], v[204:205]
	v_pk_add_f32 v[72:73], v[72:73], v[74:75]
	v_pk_add_f32 v[198:199], v[198:199], v[200:201]
	v_add_f32_e32 v142, v72, v73
	v_add_f32_e32 v143, v198, v199
	ds_read_b128 v[156:159], v124 offset:32528
	v_add_f32_dpp v142, v142, v142 quad_perm:[1,0,3,2] row_mask:0xf bank_mask:0xf bound_ctrl:1
	v_add_f32_dpp v143, v143, v143 quad_perm:[1,0,3,2] row_mask:0xf bank_mask:0xf bound_ctrl:1
	ds_read_b128 v[152:155], v124 offset:32512
	v_add_f32_dpp v142, v142, v142 quad_perm:[2,3,0,1] row_mask:0xf bank_mask:0xf bound_ctrl:1
	v_add_f32_dpp v143, v143, v143 quad_perm:[2,3,0,1] row_mask:0xf bank_mask:0xf bound_ctrl:1
	ds_read_b128 v[182:185], v124 offset:32768
	v_add_f32_dpp v142, v142, v142 row_half_mirror row_mask:0xf bank_mask:0xf bound_ctrl:1
	v_add_f32_dpp v143, v143, v143 row_half_mirror row_mask:0xf bank_mask:0xf bound_ctrl:1
	ds_read_b128 v[186:189], v124 offset:32784
	ds_read_b32 v160, v135 offset:33536
	ds_read_b128 v[190:193], v124 offset:33024
	ds_read_b128 v[194:197], v124 offset:33040
	ds_read_b128 v[144:147], v124 offset:32256
	ds_read_b128 v[148:151], v124 offset:32272
	v_pk_mul_f32 v[68:69], v[68:69], v[142:143] op_sel_hi:[1,0]
	v_pk_mul_f32 v[70:71], v[70:71], v[142:143] op_sel_hi:[1,0]
	s_mov_b32 vcc_lo, 0x8080808
	v_pk_mul_f32 v[56:57], v[56:57], v[142:143] op_sel_hi:[1,0]
	v_pk_mul_f32 v[58:59], v[58:59], v[142:143] op_sel_hi:[1,0]
	s_mov_b32 vcc_hi, 0x8080808
	v_pk_fma_f32 v[64:65], v[64:65], v[0:1], v[68:69] op_sel_hi:[1,0,1] neg_lo:[0,0,1] neg_hi:[0,0,1]
	v_pk_fma_f32 v[66:67], v[66:67], v[0:1], v[70:71] op_sel_hi:[1,0,1] neg_lo:[0,0,1] neg_hi:[0,0,1]
	v_cndmask_b32_e32 v132, v132, v143, vcc
	v_pk_fma_f32 v[60:61], v[60:61], v[0:1], v[56:57] op_sel_hi:[1,0,1] neg_lo:[0,0,1] neg_hi:[0,0,1]
	v_pk_fma_f32 v[62:63], v[62:63], v[0:1], v[58:59] op_sel_hi:[1,0,1] neg_lo:[0,0,1] neg_hi:[0,0,1]
	ds_read_b128 v[202:205], v124 offset:33296
	ds_read_b128 v[198:201], v124 offset:33280
	v_pk_fma_f32 v[36:37], v[36:37], v[48:49], v[64:65]
	v_pk_fma_f32 v[38:39], v[38:39], v[50:51], v[66:67]
	v_pk_fma_f32 v[32:33], v[32:33], v[40:41], v[60:61]
	v_pk_fma_f32 v[34:35], v[34:35], v[42:43], v[62:63]
	s_waitcnt lgkmcnt(2)
	v_pk_mul_f32 v[156:157], v[32:33], v[156:157]
	v_pk_mul_f32 v[52:53], v[32:33], v[52:53]
	v_pk_mul_f32 v[158:159], v[34:35], v[158:159]
	v_pk_mul_f32 v[54:55], v[34:35], v[54:55]
	v_pk_fma_f32 v[152:153], v[36:37], v[152:153], v[156:157]
	v_pk_fma_f32 v[44:45], v[36:37], v[44:45], v[52:53]
	v_pk_fma_f32 v[154:155], v[38:39], v[154:155], v[158:159]
	v_pk_fma_f32 v[46:47], v[38:39], v[46:47], v[54:55]
	v_pk_add_f32 v[152:153], v[152:153], v[154:155]
	v_pk_add_f32 v[44:45], v[44:45], v[46:47]
	v_add_f32_e32 v142, v152, v153
	v_add_f32_e32 v143, v44, v45
	ds_read_b128 v[76:79], v124 offset:34064
	v_add_f32_dpp v142, v142, v142 quad_perm:[1,0,3,2] row_mask:0xf bank_mask:0xf bound_ctrl:1
	v_add_f32_dpp v143, v143, v143 quad_perm:[1,0,3,2] row_mask:0xf bank_mask:0xf bound_ctrl:1
	ds_read_b128 v[72:75], v124 offset:34048
	v_add_f32_dpp v142, v142, v142 quad_perm:[2,3,0,1] row_mask:0xf bank_mask:0xf bound_ctrl:1
	v_add_f32_dpp v143, v143, v143 quad_perm:[2,3,0,1] row_mask:0xf bank_mask:0xf bound_ctrl:1
	ds_read_b128 v[68:71], v124 offset:34304
	v_add_f32_dpp v142, v142, v142 row_half_mirror row_mask:0xf bank_mask:0xf bound_ctrl:1
	v_add_f32_dpp v143, v143, v143 row_half_mirror row_mask:0xf bank_mask:0xf bound_ctrl:1
	ds_read_b128 v[56:59], v124 offset:34320
	ds_read_b32 v0, v135 offset:35072
	ds_read_b128 v[64:67], v124 offset:34560
	ds_read_b128 v[60:63], v124 offset:34576
	ds_read_b128 v[48:51], v124 offset:33792
	ds_read_b128 v[40:43], v124 offset:33808
	v_pk_mul_f32 v[182:183], v[182:183], v[142:143] op_sel_hi:[1,0]
	v_pk_mul_f32 v[184:185], v[184:185], v[142:143] op_sel_hi:[1,0]
	s_mov_b32 vcc_lo, 0x10101010
	v_pk_mul_f32 v[186:187], v[186:187], v[142:143] op_sel_hi:[1,0]
	v_pk_mul_f32 v[188:189], v[188:189], v[142:143] op_sel_hi:[1,0]
	s_mov_b32 vcc_hi, 0x10101010
	v_pk_fma_f32 v[190:191], v[190:191], v[160:161], v[182:183] op_sel_hi:[1,0,1] neg_lo:[0,0,1] neg_hi:[0,0,1]
	v_pk_fma_f32 v[192:193], v[192:193], v[160:161], v[184:185] op_sel_hi:[1,0,1] neg_lo:[0,0,1] neg_hi:[0,0,1]
	v_cndmask_b32_e32 v132, v132, v143, vcc
	v_pk_fma_f32 v[194:195], v[194:195], v[160:161], v[186:187] op_sel_hi:[1,0,1] neg_lo:[0,0,1] neg_hi:[0,0,1]
	v_pk_fma_f32 v[196:197], v[196:197], v[160:161], v[188:189] op_sel_hi:[1,0,1] neg_lo:[0,0,1] neg_hi:[0,0,1]
	ds_read_b128 v[52:55], v124 offset:34832
	ds_read_b128 v[44:47], v124 offset:34816
	v_pk_fma_f32 v[36:37], v[36:37], v[144:145], v[190:191]
	v_pk_fma_f32 v[38:39], v[38:39], v[146:147], v[192:193]
	v_pk_fma_f32 v[32:33], v[32:33], v[148:149], v[194:195]
	v_pk_fma_f32 v[34:35], v[34:35], v[150:151], v[196:197]
	s_waitcnt lgkmcnt(2)
	v_pk_mul_f32 v[76:77], v[32:33], v[76:77]
	v_pk_mul_f32 v[202:203], v[32:33], v[202:203]
	v_pk_mul_f32 v[78:79], v[34:35], v[78:79]
	v_pk_mul_f32 v[204:205], v[34:35], v[204:205]
	v_pk_fma_f32 v[72:73], v[36:37], v[72:73], v[76:77]
	v_pk_fma_f32 v[198:199], v[36:37], v[198:199], v[202:203]
	v_pk_fma_f32 v[74:75], v[38:39], v[74:75], v[78:79]
	v_pk_fma_f32 v[200:201], v[38:39], v[200:201], v[204:205]
	v_pk_add_f32 v[72:73], v[72:73], v[74:75]
	v_pk_add_f32 v[198:199], v[198:199], v[200:201]
	v_add_f32_e32 v142, v72, v73
	v_add_f32_e32 v143, v198, v199
	ds_read_b128 v[156:159], v124 offset:35600
	v_add_f32_dpp v142, v142, v142 quad_perm:[1,0,3,2] row_mask:0xf bank_mask:0xf bound_ctrl:1
	v_add_f32_dpp v143, v143, v143 quad_perm:[1,0,3,2] row_mask:0xf bank_mask:0xf bound_ctrl:1
	ds_read_b128 v[152:155], v124 offset:35584
	v_add_f32_dpp v142, v142, v142 quad_perm:[2,3,0,1] row_mask:0xf bank_mask:0xf bound_ctrl:1
	v_add_f32_dpp v143, v143, v143 quad_perm:[2,3,0,1] row_mask:0xf bank_mask:0xf bound_ctrl:1
	ds_read_b128 v[182:185], v124 offset:35840
	v_add_f32_dpp v142, v142, v142 row_half_mirror row_mask:0xf bank_mask:0xf bound_ctrl:1
	v_add_f32_dpp v143, v143, v143 row_half_mirror row_mask:0xf bank_mask:0xf bound_ctrl:1
	ds_read_b128 v[186:189], v124 offset:35856
	ds_read_b32 v160, v135 offset:36608
	ds_read_b128 v[190:193], v124 offset:36096
	ds_read_b128 v[194:197], v124 offset:36112
	ds_read_b128 v[144:147], v124 offset:35328
	ds_read_b128 v[148:151], v124 offset:35344
	v_pk_mul_f32 v[68:69], v[68:69], v[142:143] op_sel_hi:[1,0]
	v_pk_mul_f32 v[70:71], v[70:71], v[142:143] op_sel_hi:[1,0]
	s_mov_b32 vcc_lo, 0x20202020
	v_pk_mul_f32 v[56:57], v[56:57], v[142:143] op_sel_hi:[1,0]
	v_pk_mul_f32 v[58:59], v[58:59], v[142:143] op_sel_hi:[1,0]
	s_mov_b32 vcc_hi, 0x20202020
	v_pk_fma_f32 v[64:65], v[64:65], v[0:1], v[68:69] op_sel_hi:[1,0,1] neg_lo:[0,0,1] neg_hi:[0,0,1]
	v_pk_fma_f32 v[66:67], v[66:67], v[0:1], v[70:71] op_sel_hi:[1,0,1] neg_lo:[0,0,1] neg_hi:[0,0,1]
	v_cndmask_b32_e32 v132, v132, v143, vcc
	v_pk_fma_f32 v[60:61], v[60:61], v[0:1], v[56:57] op_sel_hi:[1,0,1] neg_lo:[0,0,1] neg_hi:[0,0,1]
	v_pk_fma_f32 v[62:63], v[62:63], v[0:1], v[58:59] op_sel_hi:[1,0,1] neg_lo:[0,0,1] neg_hi:[0,0,1]
	ds_read_b128 v[202:205], v124 offset:36368
	ds_read_b128 v[198:201], v124 offset:36352
	v_pk_fma_f32 v[36:37], v[36:37], v[48:49], v[64:65]
	v_pk_fma_f32 v[38:39], v[38:39], v[50:51], v[66:67]
	v_pk_fma_f32 v[32:33], v[32:33], v[40:41], v[60:61]
	v_pk_fma_f32 v[34:35], v[34:35], v[42:43], v[62:63]
	s_waitcnt lgkmcnt(2)
	v_pk_mul_f32 v[156:157], v[32:33], v[156:157]
	v_pk_mul_f32 v[52:53], v[32:33], v[52:53]
	v_pk_mul_f32 v[158:159], v[34:35], v[158:159]
	v_pk_mul_f32 v[54:55], v[34:35], v[54:55]
	v_pk_fma_f32 v[152:153], v[36:37], v[152:153], v[156:157]
	v_pk_fma_f32 v[44:45], v[36:37], v[44:45], v[52:53]
	v_pk_fma_f32 v[154:155], v[38:39], v[154:155], v[158:159]
	v_pk_fma_f32 v[46:47], v[38:39], v[46:47], v[54:55]
	v_pk_add_f32 v[152:153], v[152:153], v[154:155]
	v_pk_add_f32 v[44:45], v[44:45], v[46:47]
	v_add_f32_e32 v142, v152, v153
	v_add_f32_e32 v143, v44, v45
	ds_read_b128 v[76:79], v124 offset:37136
	v_add_f32_dpp v142, v142, v142 quad_perm:[1,0,3,2] row_mask:0xf bank_mask:0xf bound_ctrl:1
	v_add_f32_dpp v143, v143, v143 quad_perm:[1,0,3,2] row_mask:0xf bank_mask:0xf bound_ctrl:1
	ds_read_b128 v[72:75], v124 offset:37120
	v_add_f32_dpp v142, v142, v142 quad_perm:[2,3,0,1] row_mask:0xf bank_mask:0xf bound_ctrl:1
	v_add_f32_dpp v143, v143, v143 quad_perm:[2,3,0,1] row_mask:0xf bank_mask:0xf bound_ctrl:1
	ds_read_b128 v[68:71], v124 offset:37376
	v_add_f32_dpp v142, v142, v142 row_half_mirror row_mask:0xf bank_mask:0xf bound_ctrl:1
	v_add_f32_dpp v143, v143, v143 row_half_mirror row_mask:0xf bank_mask:0xf bound_ctrl:1
	ds_read_b128 v[56:59], v124 offset:37392
	ds_read_b32 v0, v135 offset:38144
	ds_read_b128 v[64:67], v124 offset:37632
	ds_read_b128 v[60:63], v124 offset:37648
	ds_read_b128 v[48:51], v124 offset:36864
	ds_read_b128 v[40:43], v124 offset:36880
	v_pk_mul_f32 v[182:183], v[182:183], v[142:143] op_sel_hi:[1,0]
	v_pk_mul_f32 v[184:185], v[184:185], v[142:143] op_sel_hi:[1,0]
	s_mov_b32 vcc_lo, 0x40404040
	v_pk_mul_f32 v[186:187], v[186:187], v[142:143] op_sel_hi:[1,0]
	v_pk_mul_f32 v[188:189], v[188:189], v[142:143] op_sel_hi:[1,0]
	s_mov_b32 vcc_hi, 0x40404040
	v_pk_fma_f32 v[190:191], v[190:191], v[160:161], v[182:183] op_sel_hi:[1,0,1] neg_lo:[0,0,1] neg_hi:[0,0,1]
	v_pk_fma_f32 v[192:193], v[192:193], v[160:161], v[184:185] op_sel_hi:[1,0,1] neg_lo:[0,0,1] neg_hi:[0,0,1]
	v_cndmask_b32_e32 v132, v132, v143, vcc
	v_pk_fma_f32 v[194:195], v[194:195], v[160:161], v[186:187] op_sel_hi:[1,0,1] neg_lo:[0,0,1] neg_hi:[0,0,1]
	v_pk_fma_f32 v[196:197], v[196:197], v[160:161], v[188:189] op_sel_hi:[1,0,1] neg_lo:[0,0,1] neg_hi:[0,0,1]
	ds_read_b128 v[52:55], v124 offset:37904
	ds_read_b128 v[44:47], v124 offset:37888
	v_pk_fma_f32 v[36:37], v[36:37], v[144:145], v[190:191]
	v_pk_fma_f32 v[38:39], v[38:39], v[146:147], v[192:193]
	v_pk_fma_f32 v[32:33], v[32:33], v[148:149], v[194:195]
	v_pk_fma_f32 v[34:35], v[34:35], v[150:151], v[196:197]
	s_waitcnt lgkmcnt(2)
	v_pk_mul_f32 v[76:77], v[32:33], v[76:77]
	v_pk_mul_f32 v[202:203], v[32:33], v[202:203]
	v_pk_mul_f32 v[78:79], v[34:35], v[78:79]
	v_pk_mul_f32 v[204:205], v[34:35], v[204:205]
	v_pk_fma_f32 v[72:73], v[36:37], v[72:73], v[76:77]
	v_pk_fma_f32 v[198:199], v[36:37], v[198:199], v[202:203]
	v_pk_fma_f32 v[74:75], v[38:39], v[74:75], v[78:79]
	v_pk_fma_f32 v[200:201], v[38:39], v[200:201], v[204:205]
	v_pk_add_f32 v[72:73], v[72:73], v[74:75]
	v_pk_add_f32 v[198:199], v[198:199], v[200:201]
	v_add_f32_e32 v142, v72, v73
	v_add_f32_e32 v143, v198, v199
	ds_read_b128 v[156:159], v124 offset:38672
	v_add_f32_dpp v142, v142, v142 quad_perm:[1,0,3,2] row_mask:0xf bank_mask:0xf bound_ctrl:1
	v_add_f32_dpp v143, v143, v143 quad_perm:[1,0,3,2] row_mask:0xf bank_mask:0xf bound_ctrl:1
	ds_read_b128 v[152:155], v124 offset:38656
	v_add_f32_dpp v142, v142, v142 quad_perm:[2,3,0,1] row_mask:0xf bank_mask:0xf bound_ctrl:1
	v_add_f32_dpp v143, v143, v143 quad_perm:[2,3,0,1] row_mask:0xf bank_mask:0xf bound_ctrl:1
	ds_read_b128 v[182:185], v124 offset:38912
	v_add_f32_dpp v142, v142, v142 row_half_mirror row_mask:0xf bank_mask:0xf bound_ctrl:1
	v_add_f32_dpp v143, v143, v143 row_half_mirror row_mask:0xf bank_mask:0xf bound_ctrl:1
	ds_read_b128 v[186:189], v124 offset:38928
	ds_read_b32 v160, v135 offset:39680
	ds_read_b128 v[190:193], v124 offset:39168
	ds_read_b128 v[194:197], v124 offset:39184
	ds_read_b128 v[144:147], v124 offset:38400
	ds_read_b128 v[148:151], v124 offset:38416
	v_pk_mul_f32 v[68:69], v[68:69], v[142:143] op_sel_hi:[1,0]
	v_pk_mul_f32 v[70:71], v[70:71], v[142:143] op_sel_hi:[1,0]
	s_mov_b32 vcc_lo, 0x80808080
	v_pk_mul_f32 v[56:57], v[56:57], v[142:143] op_sel_hi:[1,0]
	v_pk_mul_f32 v[58:59], v[58:59], v[142:143] op_sel_hi:[1,0]
	s_mov_b32 vcc_hi, 0x80808080
	v_pk_fma_f32 v[64:65], v[64:65], v[0:1], v[68:69] op_sel_hi:[1,0,1] neg_lo:[0,0,1] neg_hi:[0,0,1]
	v_pk_fma_f32 v[66:67], v[66:67], v[0:1], v[70:71] op_sel_hi:[1,0,1] neg_lo:[0,0,1] neg_hi:[0,0,1]
	v_cndmask_b32_e32 v132, v132, v143, vcc
	v_pk_fma_f32 v[60:61], v[60:61], v[0:1], v[56:57] op_sel_hi:[1,0,1] neg_lo:[0,0,1] neg_hi:[0,0,1]
	v_pk_fma_f32 v[62:63], v[62:63], v[0:1], v[58:59] op_sel_hi:[1,0,1] neg_lo:[0,0,1] neg_hi:[0,0,1]
	ds_read_b128 v[202:205], v124 offset:39440
	ds_read_b128 v[198:201], v124 offset:39424
	v_pk_fma_f32 v[36:37], v[36:37], v[48:49], v[64:65]
	v_pk_fma_f32 v[38:39], v[38:39], v[50:51], v[66:67]
	v_pk_fma_f32 v[32:33], v[32:33], v[40:41], v[60:61]
	v_pk_fma_f32 v[34:35], v[34:35], v[42:43], v[62:63]
	s_waitcnt lgkmcnt(2)
	v_pk_mul_f32 v[156:157], v[32:33], v[156:157]
	v_pk_mul_f32 v[52:53], v[32:33], v[52:53]
	v_pk_mul_f32 v[158:159], v[34:35], v[158:159]
	v_pk_mul_f32 v[54:55], v[34:35], v[54:55]
	v_pk_fma_f32 v[152:153], v[36:37], v[152:153], v[156:157]
	v_pk_fma_f32 v[44:45], v[36:37], v[44:45], v[52:53]
	v_pk_fma_f32 v[154:155], v[38:39], v[154:155], v[158:159]
	v_pk_fma_f32 v[46:47], v[38:39], v[46:47], v[54:55]
	v_pk_add_f32 v[152:153], v[152:153], v[154:155]
	v_pk_add_f32 v[44:45], v[44:45], v[46:47]
	v_add_f32_e32 v142, v152, v153
	v_add_f32_e32 v143, v44, v45
	ds_read_b128 v[76:79], v124 offset:40208
	v_add_f32_dpp v142, v142, v142 quad_perm:[1,0,3,2] row_mask:0xf bank_mask:0xf bound_ctrl:1
	v_add_f32_dpp v143, v143, v143 quad_perm:[1,0,3,2] row_mask:0xf bank_mask:0xf bound_ctrl:1
	ds_read_b128 v[72:75], v124 offset:40192
	v_add_f32_dpp v142, v142, v142 quad_perm:[2,3,0,1] row_mask:0xf bank_mask:0xf bound_ctrl:1
	v_add_f32_dpp v143, v143, v143 quad_perm:[2,3,0,1] row_mask:0xf bank_mask:0xf bound_ctrl:1
	ds_read_b128 v[68:71], v124 offset:40448
	v_add_f32_dpp v142, v142, v142 row_half_mirror row_mask:0xf bank_mask:0xf bound_ctrl:1
	v_add_f32_dpp v143, v143, v143 row_half_mirror row_mask:0xf bank_mask:0xf bound_ctrl:1
	ds_read_b128 v[56:59], v124 offset:40464
	ds_read_b32 v0, v135 offset:41216
	ds_read_b128 v[64:67], v124 offset:40704
	ds_read_b128 v[60:63], v124 offset:40720
	ds_read_b128 v[48:51], v124 offset:39936
	ds_read_b128 v[40:43], v124 offset:39952
	v_pk_mul_f32 v[182:183], v[182:183], v[142:143] op_sel_hi:[1,0]
	v_pk_mul_f32 v[184:185], v[184:185], v[142:143] op_sel_hi:[1,0]
	s_mov_b32 vcc_lo, 0x1010101
	v_pk_mul_f32 v[186:187], v[186:187], v[142:143] op_sel_hi:[1,0]
	v_pk_mul_f32 v[188:189], v[188:189], v[142:143] op_sel_hi:[1,0]
	s_mov_b32 vcc_hi, 0x1010101
	v_pk_fma_f32 v[190:191], v[190:191], v[160:161], v[182:183] op_sel_hi:[1,0,1] neg_lo:[0,0,1] neg_hi:[0,0,1]
	v_pk_fma_f32 v[192:193], v[192:193], v[160:161], v[184:185] op_sel_hi:[1,0,1] neg_lo:[0,0,1] neg_hi:[0,0,1]
	v_cndmask_b32_e32 v131, v131, v143, vcc
	v_pk_fma_f32 v[194:195], v[194:195], v[160:161], v[186:187] op_sel_hi:[1,0,1] neg_lo:[0,0,1] neg_hi:[0,0,1]
	v_pk_fma_f32 v[196:197], v[196:197], v[160:161], v[188:189] op_sel_hi:[1,0,1] neg_lo:[0,0,1] neg_hi:[0,0,1]
	ds_read_b128 v[52:55], v124 offset:40976
	ds_read_b128 v[44:47], v124 offset:40960
	v_pk_fma_f32 v[36:37], v[36:37], v[144:145], v[190:191]
	v_pk_fma_f32 v[38:39], v[38:39], v[146:147], v[192:193]
	v_pk_fma_f32 v[32:33], v[32:33], v[148:149], v[194:195]
	v_pk_fma_f32 v[34:35], v[34:35], v[150:151], v[196:197]
	s_waitcnt lgkmcnt(2)
	v_pk_mul_f32 v[76:77], v[32:33], v[76:77]
	v_pk_mul_f32 v[202:203], v[32:33], v[202:203]
	v_pk_mul_f32 v[78:79], v[34:35], v[78:79]
	v_pk_mul_f32 v[204:205], v[34:35], v[204:205]
	v_pk_fma_f32 v[72:73], v[36:37], v[72:73], v[76:77]
	v_pk_fma_f32 v[198:199], v[36:37], v[198:199], v[202:203]
	v_pk_fma_f32 v[74:75], v[38:39], v[74:75], v[78:79]
	v_pk_fma_f32 v[200:201], v[38:39], v[200:201], v[204:205]
	v_pk_add_f32 v[72:73], v[72:73], v[74:75]
	v_pk_add_f32 v[198:199], v[198:199], v[200:201]
	v_add_f32_e32 v142, v72, v73
	v_add_f32_e32 v143, v198, v199
	ds_read_b128 v[156:159], v124 offset:41744
	v_add_f32_dpp v142, v142, v142 quad_perm:[1,0,3,2] row_mask:0xf bank_mask:0xf bound_ctrl:1
	v_add_f32_dpp v143, v143, v143 quad_perm:[1,0,3,2] row_mask:0xf bank_mask:0xf bound_ctrl:1
	ds_read_b128 v[152:155], v124 offset:41728
	v_add_f32_dpp v142, v142, v142 quad_perm:[2,3,0,1] row_mask:0xf bank_mask:0xf bound_ctrl:1
	v_add_f32_dpp v143, v143, v143 quad_perm:[2,3,0,1] row_mask:0xf bank_mask:0xf bound_ctrl:1
	ds_read_b128 v[182:185], v124 offset:41984
	v_add_f32_dpp v142, v142, v142 row_half_mirror row_mask:0xf bank_mask:0xf bound_ctrl:1
	v_add_f32_dpp v143, v143, v143 row_half_mirror row_mask:0xf bank_mask:0xf bound_ctrl:1
	ds_read_b128 v[186:189], v124 offset:42000
	ds_read_b32 v160, v135 offset:42752
	ds_read_b128 v[190:193], v124 offset:42240
	ds_read_b128 v[194:197], v124 offset:42256
	ds_read_b128 v[144:147], v124 offset:41472
	ds_read_b128 v[148:151], v124 offset:41488
	v_pk_mul_f32 v[68:69], v[68:69], v[142:143] op_sel_hi:[1,0]
	v_pk_mul_f32 v[70:71], v[70:71], v[142:143] op_sel_hi:[1,0]
	s_mov_b32 vcc_lo, 0x2020202
	v_pk_mul_f32 v[56:57], v[56:57], v[142:143] op_sel_hi:[1,0]
	v_pk_mul_f32 v[58:59], v[58:59], v[142:143] op_sel_hi:[1,0]
	s_mov_b32 vcc_hi, 0x2020202
	v_pk_fma_f32 v[64:65], v[64:65], v[0:1], v[68:69] op_sel_hi:[1,0,1] neg_lo:[0,0,1] neg_hi:[0,0,1]
	v_pk_fma_f32 v[66:67], v[66:67], v[0:1], v[70:71] op_sel_hi:[1,0,1] neg_lo:[0,0,1] neg_hi:[0,0,1]
	v_cndmask_b32_e32 v131, v131, v143, vcc
	v_pk_fma_f32 v[60:61], v[60:61], v[0:1], v[56:57] op_sel_hi:[1,0,1] neg_lo:[0,0,1] neg_hi:[0,0,1]
	v_pk_fma_f32 v[62:63], v[62:63], v[0:1], v[58:59] op_sel_hi:[1,0,1] neg_lo:[0,0,1] neg_hi:[0,0,1]
	ds_read_b128 v[202:205], v124 offset:42512
	ds_read_b128 v[198:201], v124 offset:42496
	v_pk_fma_f32 v[36:37], v[36:37], v[48:49], v[64:65]
	v_pk_fma_f32 v[38:39], v[38:39], v[50:51], v[66:67]
	v_pk_fma_f32 v[32:33], v[32:33], v[40:41], v[60:61]
	v_pk_fma_f32 v[34:35], v[34:35], v[42:43], v[62:63]
	s_waitcnt lgkmcnt(2)
	v_pk_mul_f32 v[156:157], v[32:33], v[156:157]
	v_pk_mul_f32 v[52:53], v[32:33], v[52:53]
	v_pk_mul_f32 v[158:159], v[34:35], v[158:159]
	v_pk_mul_f32 v[54:55], v[34:35], v[54:55]
	v_pk_fma_f32 v[152:153], v[36:37], v[152:153], v[156:157]
	v_pk_fma_f32 v[44:45], v[36:37], v[44:45], v[52:53]
	v_pk_fma_f32 v[154:155], v[38:39], v[154:155], v[158:159]
	v_pk_fma_f32 v[46:47], v[38:39], v[46:47], v[54:55]
	v_pk_add_f32 v[152:153], v[152:153], v[154:155]
	v_pk_add_f32 v[44:45], v[44:45], v[46:47]
	v_add_f32_e32 v142, v152, v153
	v_add_f32_e32 v143, v44, v45
	ds_read_b128 v[76:79], v124 offset:43280
	v_add_f32_dpp v142, v142, v142 quad_perm:[1,0,3,2] row_mask:0xf bank_mask:0xf bound_ctrl:1
	v_add_f32_dpp v143, v143, v143 quad_perm:[1,0,3,2] row_mask:0xf bank_mask:0xf bound_ctrl:1
	ds_read_b128 v[72:75], v124 offset:43264
	v_add_f32_dpp v142, v142, v142 quad_perm:[2,3,0,1] row_mask:0xf bank_mask:0xf bound_ctrl:1
	v_add_f32_dpp v143, v143, v143 quad_perm:[2,3,0,1] row_mask:0xf bank_mask:0xf bound_ctrl:1
	ds_read_b128 v[68:71], v124 offset:43520
	v_add_f32_dpp v142, v142, v142 row_half_mirror row_mask:0xf bank_mask:0xf bound_ctrl:1
	v_add_f32_dpp v143, v143, v143 row_half_mirror row_mask:0xf bank_mask:0xf bound_ctrl:1
	ds_read_b128 v[56:59], v124 offset:43536
	ds_read_b32 v0, v135 offset:44288
	ds_read_b128 v[64:67], v124 offset:43776
	ds_read_b128 v[60:63], v124 offset:43792
	ds_read_b128 v[48:51], v124 offset:43008
	ds_read_b128 v[40:43], v124 offset:43024
	v_pk_mul_f32 v[182:183], v[182:183], v[142:143] op_sel_hi:[1,0]
	v_pk_mul_f32 v[184:185], v[184:185], v[142:143] op_sel_hi:[1,0]
	s_mov_b32 vcc_lo, 0x4040404
	v_pk_mul_f32 v[186:187], v[186:187], v[142:143] op_sel_hi:[1,0]
	v_pk_mul_f32 v[188:189], v[188:189], v[142:143] op_sel_hi:[1,0]
	s_mov_b32 vcc_hi, 0x4040404
	v_pk_fma_f32 v[190:191], v[190:191], v[160:161], v[182:183] op_sel_hi:[1,0,1] neg_lo:[0,0,1] neg_hi:[0,0,1]
	v_pk_fma_f32 v[192:193], v[192:193], v[160:161], v[184:185] op_sel_hi:[1,0,1] neg_lo:[0,0,1] neg_hi:[0,0,1]
	v_cndmask_b32_e32 v131, v131, v143, vcc
	v_pk_fma_f32 v[194:195], v[194:195], v[160:161], v[186:187] op_sel_hi:[1,0,1] neg_lo:[0,0,1] neg_hi:[0,0,1]
	v_pk_fma_f32 v[196:197], v[196:197], v[160:161], v[188:189] op_sel_hi:[1,0,1] neg_lo:[0,0,1] neg_hi:[0,0,1]
	ds_read_b128 v[52:55], v124 offset:44048
	ds_read_b128 v[44:47], v124 offset:44032
	v_pk_fma_f32 v[36:37], v[36:37], v[144:145], v[190:191]
	v_pk_fma_f32 v[38:39], v[38:39], v[146:147], v[192:193]
	v_pk_fma_f32 v[32:33], v[32:33], v[148:149], v[194:195]
	v_pk_fma_f32 v[34:35], v[34:35], v[150:151], v[196:197]
	s_waitcnt lgkmcnt(2)
	v_pk_mul_f32 v[76:77], v[32:33], v[76:77]
	v_pk_mul_f32 v[202:203], v[32:33], v[202:203]
	v_pk_mul_f32 v[78:79], v[34:35], v[78:79]
	v_pk_mul_f32 v[204:205], v[34:35], v[204:205]
	v_pk_fma_f32 v[72:73], v[36:37], v[72:73], v[76:77]
	v_pk_fma_f32 v[198:199], v[36:37], v[198:199], v[202:203]
	v_pk_fma_f32 v[74:75], v[38:39], v[74:75], v[78:79]
	v_pk_fma_f32 v[200:201], v[38:39], v[200:201], v[204:205]
	v_pk_add_f32 v[72:73], v[72:73], v[74:75]
	v_pk_add_f32 v[198:199], v[198:199], v[200:201]
	v_add_f32_e32 v142, v72, v73
	v_add_f32_e32 v143, v198, v199
	ds_read_b128 v[156:159], v124 offset:44816
	v_add_f32_dpp v142, v142, v142 quad_perm:[1,0,3,2] row_mask:0xf bank_mask:0xf bound_ctrl:1
	v_add_f32_dpp v143, v143, v143 quad_perm:[1,0,3,2] row_mask:0xf bank_mask:0xf bound_ctrl:1
	ds_read_b128 v[152:155], v124 offset:44800
	v_add_f32_dpp v142, v142, v142 quad_perm:[2,3,0,1] row_mask:0xf bank_mask:0xf bound_ctrl:1
	v_add_f32_dpp v143, v143, v143 quad_perm:[2,3,0,1] row_mask:0xf bank_mask:0xf bound_ctrl:1
	ds_read_b128 v[182:185], v124 offset:45056
	v_add_f32_dpp v142, v142, v142 row_half_mirror row_mask:0xf bank_mask:0xf bound_ctrl:1
	v_add_f32_dpp v143, v143, v143 row_half_mirror row_mask:0xf bank_mask:0xf bound_ctrl:1
	ds_read_b128 v[186:189], v124 offset:45072
	ds_read_b32 v160, v135 offset:45824
	ds_read_b128 v[190:193], v124 offset:45312
	ds_read_b128 v[194:197], v124 offset:45328
	ds_read_b128 v[144:147], v124 offset:44544
	ds_read_b128 v[148:151], v124 offset:44560
	v_pk_mul_f32 v[68:69], v[68:69], v[142:143] op_sel_hi:[1,0]
	v_pk_mul_f32 v[70:71], v[70:71], v[142:143] op_sel_hi:[1,0]
	s_mov_b32 vcc_lo, 0x8080808
	v_pk_mul_f32 v[56:57], v[56:57], v[142:143] op_sel_hi:[1,0]
	v_pk_mul_f32 v[58:59], v[58:59], v[142:143] op_sel_hi:[1,0]
	s_mov_b32 vcc_hi, 0x8080808
	v_pk_fma_f32 v[64:65], v[64:65], v[0:1], v[68:69] op_sel_hi:[1,0,1] neg_lo:[0,0,1] neg_hi:[0,0,1]
	v_pk_fma_f32 v[66:67], v[66:67], v[0:1], v[70:71] op_sel_hi:[1,0,1] neg_lo:[0,0,1] neg_hi:[0,0,1]
	v_cndmask_b32_e32 v131, v131, v143, vcc
	v_pk_fma_f32 v[60:61], v[60:61], v[0:1], v[56:57] op_sel_hi:[1,0,1] neg_lo:[0,0,1] neg_hi:[0,0,1]
	v_pk_fma_f32 v[62:63], v[62:63], v[0:1], v[58:59] op_sel_hi:[1,0,1] neg_lo:[0,0,1] neg_hi:[0,0,1]
	ds_read_b128 v[202:205], v124 offset:45584
	ds_read_b128 v[198:201], v124 offset:45568
	v_pk_fma_f32 v[36:37], v[36:37], v[48:49], v[64:65]
	v_pk_fma_f32 v[38:39], v[38:39], v[50:51], v[66:67]
	v_pk_fma_f32 v[32:33], v[32:33], v[40:41], v[60:61]
	v_pk_fma_f32 v[34:35], v[34:35], v[42:43], v[62:63]
	s_waitcnt lgkmcnt(2)
	v_pk_mul_f32 v[156:157], v[32:33], v[156:157]
	v_pk_mul_f32 v[52:53], v[32:33], v[52:53]
	v_pk_mul_f32 v[158:159], v[34:35], v[158:159]
	v_pk_mul_f32 v[54:55], v[34:35], v[54:55]
	v_pk_fma_f32 v[152:153], v[36:37], v[152:153], v[156:157]
	v_pk_fma_f32 v[44:45], v[36:37], v[44:45], v[52:53]
	v_pk_fma_f32 v[154:155], v[38:39], v[154:155], v[158:159]
	v_pk_fma_f32 v[46:47], v[38:39], v[46:47], v[54:55]
	v_pk_add_f32 v[152:153], v[152:153], v[154:155]
	v_pk_add_f32 v[44:45], v[44:45], v[46:47]
	v_add_f32_e32 v142, v152, v153
	v_add_f32_e32 v143, v44, v45
	ds_read_b128 v[76:79], v124 offset:46352
	v_add_f32_dpp v142, v142, v142 quad_perm:[1,0,3,2] row_mask:0xf bank_mask:0xf bound_ctrl:1
	v_add_f32_dpp v143, v143, v143 quad_perm:[1,0,3,2] row_mask:0xf bank_mask:0xf bound_ctrl:1
	ds_read_b128 v[72:75], v124 offset:46336
	v_add_f32_dpp v142, v142, v142 quad_perm:[2,3,0,1] row_mask:0xf bank_mask:0xf bound_ctrl:1
	v_add_f32_dpp v143, v143, v143 quad_perm:[2,3,0,1] row_mask:0xf bank_mask:0xf bound_ctrl:1
	ds_read_b128 v[68:71], v124 offset:46592
	v_add_f32_dpp v142, v142, v142 row_half_mirror row_mask:0xf bank_mask:0xf bound_ctrl:1
	v_add_f32_dpp v143, v143, v143 row_half_mirror row_mask:0xf bank_mask:0xf bound_ctrl:1
	ds_read_b128 v[56:59], v124 offset:46608
	ds_read_b32 v0, v135 offset:47360
	ds_read_b128 v[64:67], v124 offset:46848
	ds_read_b128 v[60:63], v124 offset:46864
	ds_read_b128 v[48:51], v124 offset:46080
	ds_read_b128 v[40:43], v124 offset:46096
	v_pk_mul_f32 v[182:183], v[182:183], v[142:143] op_sel_hi:[1,0]
	v_pk_mul_f32 v[184:185], v[184:185], v[142:143] op_sel_hi:[1,0]
	s_mov_b32 vcc_lo, 0x10101010
	v_pk_mul_f32 v[186:187], v[186:187], v[142:143] op_sel_hi:[1,0]
	v_pk_mul_f32 v[188:189], v[188:189], v[142:143] op_sel_hi:[1,0]
	s_mov_b32 vcc_hi, 0x10101010
	v_pk_fma_f32 v[190:191], v[190:191], v[160:161], v[182:183] op_sel_hi:[1,0,1] neg_lo:[0,0,1] neg_hi:[0,0,1]
	v_pk_fma_f32 v[192:193], v[192:193], v[160:161], v[184:185] op_sel_hi:[1,0,1] neg_lo:[0,0,1] neg_hi:[0,0,1]
	v_cndmask_b32_e32 v131, v131, v143, vcc
	v_pk_fma_f32 v[194:195], v[194:195], v[160:161], v[186:187] op_sel_hi:[1,0,1] neg_lo:[0,0,1] neg_hi:[0,0,1]
	v_pk_fma_f32 v[196:197], v[196:197], v[160:161], v[188:189] op_sel_hi:[1,0,1] neg_lo:[0,0,1] neg_hi:[0,0,1]
	ds_read_b128 v[52:55], v124 offset:47120
	ds_read_b128 v[44:47], v124 offset:47104
	v_pk_fma_f32 v[36:37], v[36:37], v[144:145], v[190:191]
	v_pk_fma_f32 v[38:39], v[38:39], v[146:147], v[192:193]
	v_pk_fma_f32 v[32:33], v[32:33], v[148:149], v[194:195]
	v_pk_fma_f32 v[34:35], v[34:35], v[150:151], v[196:197]
	s_waitcnt lgkmcnt(2)
	v_pk_mul_f32 v[76:77], v[32:33], v[76:77]
	v_pk_mul_f32 v[202:203], v[32:33], v[202:203]
	v_pk_mul_f32 v[78:79], v[34:35], v[78:79]
	v_pk_mul_f32 v[204:205], v[34:35], v[204:205]
	v_pk_fma_f32 v[72:73], v[36:37], v[72:73], v[76:77]
	v_pk_fma_f32 v[198:199], v[36:37], v[198:199], v[202:203]
	v_pk_fma_f32 v[74:75], v[38:39], v[74:75], v[78:79]
	v_pk_fma_f32 v[200:201], v[38:39], v[200:201], v[204:205]
	v_pk_add_f32 v[72:73], v[72:73], v[74:75]
	v_pk_add_f32 v[198:199], v[198:199], v[200:201]
	v_add_f32_e32 v142, v72, v73
	v_add_f32_e32 v143, v198, v199
	ds_read_b128 v[156:159], v124 offset:47888
	v_add_f32_dpp v142, v142, v142 quad_perm:[1,0,3,2] row_mask:0xf bank_mask:0xf bound_ctrl:1
	v_add_f32_dpp v143, v143, v143 quad_perm:[1,0,3,2] row_mask:0xf bank_mask:0xf bound_ctrl:1
	ds_read_b128 v[152:155], v124 offset:47872
	v_add_f32_dpp v142, v142, v142 quad_perm:[2,3,0,1] row_mask:0xf bank_mask:0xf bound_ctrl:1
	v_add_f32_dpp v143, v143, v143 quad_perm:[2,3,0,1] row_mask:0xf bank_mask:0xf bound_ctrl:1
	ds_read_b128 v[182:185], v124 offset:48128
	v_add_f32_dpp v142, v142, v142 row_half_mirror row_mask:0xf bank_mask:0xf bound_ctrl:1
	v_add_f32_dpp v143, v143, v143 row_half_mirror row_mask:0xf bank_mask:0xf bound_ctrl:1
	ds_read_b128 v[186:189], v124 offset:48144
	ds_read_b32 v160, v135 offset:48896
	ds_read_b128 v[190:193], v124 offset:48384
	ds_read_b128 v[194:197], v124 offset:48400
	ds_read_b128 v[144:147], v124 offset:47616
	ds_read_b128 v[148:151], v124 offset:47632
	v_pk_mul_f32 v[68:69], v[68:69], v[142:143] op_sel_hi:[1,0]
	v_pk_mul_f32 v[70:71], v[70:71], v[142:143] op_sel_hi:[1,0]
	s_mov_b32 vcc_lo, 0x20202020
	v_pk_mul_f32 v[56:57], v[56:57], v[142:143] op_sel_hi:[1,0]
	v_pk_mul_f32 v[58:59], v[58:59], v[142:143] op_sel_hi:[1,0]
	s_mov_b32 vcc_hi, 0x20202020
	v_pk_fma_f32 v[64:65], v[64:65], v[0:1], v[68:69] op_sel_hi:[1,0,1] neg_lo:[0,0,1] neg_hi:[0,0,1]
	v_pk_fma_f32 v[66:67], v[66:67], v[0:1], v[70:71] op_sel_hi:[1,0,1] neg_lo:[0,0,1] neg_hi:[0,0,1]
	v_cndmask_b32_e32 v131, v131, v143, vcc
	v_pk_fma_f32 v[60:61], v[60:61], v[0:1], v[56:57] op_sel_hi:[1,0,1] neg_lo:[0,0,1] neg_hi:[0,0,1]
	v_pk_fma_f32 v[62:63], v[62:63], v[0:1], v[58:59] op_sel_hi:[1,0,1] neg_lo:[0,0,1] neg_hi:[0,0,1]
	ds_read_b128 v[202:205], v124 offset:48656
	ds_read_b128 v[198:201], v124 offset:48640
	v_pk_fma_f32 v[36:37], v[36:37], v[48:49], v[64:65]
	v_pk_fma_f32 v[38:39], v[38:39], v[50:51], v[66:67]
	v_pk_fma_f32 v[32:33], v[32:33], v[40:41], v[60:61]
	v_pk_fma_f32 v[34:35], v[34:35], v[42:43], v[62:63]
	s_waitcnt lgkmcnt(2)
	v_pk_mul_f32 v[156:157], v[32:33], v[156:157]
	v_pk_mul_f32 v[52:53], v[32:33], v[52:53]
	v_pk_mul_f32 v[158:159], v[34:35], v[158:159]
	v_pk_mul_f32 v[54:55], v[34:35], v[54:55]
	v_pk_fma_f32 v[152:153], v[36:37], v[152:153], v[156:157]
	v_pk_fma_f32 v[44:45], v[36:37], v[44:45], v[52:53]
	v_pk_fma_f32 v[154:155], v[38:39], v[154:155], v[158:159]
	v_pk_fma_f32 v[46:47], v[38:39], v[46:47], v[54:55]
	v_pk_add_f32 v[152:153], v[152:153], v[154:155]
	v_pk_add_f32 v[44:45], v[44:45], v[46:47]
	v_add_f32_e32 v142, v152, v153
	v_add_f32_e32 v143, v44, v45
	s_nop 0
	v_add_f32_dpp v142, v142, v142 quad_perm:[1,0,3,2] row_mask:0xf bank_mask:0xf bound_ctrl:1
	v_add_f32_dpp v143, v143, v143 quad_perm:[1,0,3,2] row_mask:0xf bank_mask:0xf bound_ctrl:1
	s_nop 0
	v_add_f32_dpp v142, v142, v142 quad_perm:[2,3,0,1] row_mask:0xf bank_mask:0xf bound_ctrl:1
	v_add_f32_dpp v143, v143, v143 quad_perm:[2,3,0,1] row_mask:0xf bank_mask:0xf bound_ctrl:1
	s_nop 0
	v_add_f32_dpp v142, v142, v142 row_half_mirror row_mask:0xf bank_mask:0xf bound_ctrl:1
	v_add_f32_dpp v143, v143, v143 row_half_mirror row_mask:0xf bank_mask:0xf bound_ctrl:1
	v_pk_mul_f32 v[182:183], v[182:183], v[142:143] op_sel_hi:[1,0]
	v_pk_mul_f32 v[184:185], v[184:185], v[142:143] op_sel_hi:[1,0]
	s_mov_b32 vcc_lo, 0x40404040
	v_pk_mul_f32 v[186:187], v[186:187], v[142:143] op_sel_hi:[1,0]
	v_pk_mul_f32 v[188:189], v[188:189], v[142:143] op_sel_hi:[1,0]
	s_mov_b32 vcc_hi, 0x40404040
	v_pk_fma_f32 v[190:191], v[190:191], v[160:161], v[182:183] op_sel_hi:[1,0,1] neg_lo:[0,0,1] neg_hi:[0,0,1]
	v_pk_fma_f32 v[192:193], v[192:193], v[160:161], v[184:185] op_sel_hi:[1,0,1] neg_lo:[0,0,1] neg_hi:[0,0,1]
	v_cndmask_b32_e32 v131, v131, v143, vcc
	v_pk_fma_f32 v[194:195], v[194:195], v[160:161], v[186:187] op_sel_hi:[1,0,1] neg_lo:[0,0,1] neg_hi:[0,0,1]
	v_pk_fma_f32 v[196:197], v[196:197], v[160:161], v[188:189] op_sel_hi:[1,0,1] neg_lo:[0,0,1] neg_hi:[0,0,1]
	v_pk_fma_f32 v[36:37], v[36:37], v[144:145], v[190:191]
	v_pk_fma_f32 v[38:39], v[38:39], v[146:147], v[192:193]
	v_pk_fma_f32 v[32:33], v[32:33], v[148:149], v[194:195]
	v_pk_fma_f32 v[34:35], v[34:35], v[150:151], v[196:197]
	s_waitcnt lgkmcnt(0)
	v_pk_mul_f32 v[202:203], v[32:33], v[202:203]
	v_pk_mul_f32 v[204:205], v[34:35], v[204:205]
	v_pk_fma_f32 v[198:199], v[36:37], v[198:199], v[202:203]
	v_pk_fma_f32 v[200:201], v[38:39], v[200:201], v[204:205]
	v_pk_add_f32 v[198:199], v[198:199], v[200:201]
	v_add_f32_e32 v143, v198, v199
	s_nop 1
	v_add_f32_dpp v143, v143, v143 quad_perm:[1,0,3,2] row_mask:0xf bank_mask:0xf bound_ctrl:1
	s_nop 1
	v_add_f32_dpp v143, v143, v143 quad_perm:[2,3,0,1] row_mask:0xf bank_mask:0xf bound_ctrl:1
	s_nop 1
	v_add_f32_dpp v143, v143, v143 row_half_mirror row_mask:0xf bank_mask:0xf bound_ctrl:1
	s_mov_b32 vcc_lo, 0x80808080
	s_mov_b32 vcc_hi, 0x80808080
	v_cndmask_b32_e32 v131, v131, v143, vcc
